# GQA attention loop: wave halves ping-ponged inside the same instruction stream (waves 0-3 rendezvous after softmax, waves 4-7 after QK; K/V DMA per block = K(t+2), V(t+1)), so one half's P+Q MFMA run
# speedup vs baseline: 1.0083x; 1.0083x over previous
.LBB0_285:
	s_lshl_b32 s11, s11, 6
	s_and_b32 s11, s11, 0x100
	s_add_u32 s12, s18, s11
	s_addc_u32 s13, s19, 0
	s_add_u32 s14, s20, s11
	s_addc_u32 s15, s21, 0
	s_ashr_i32 s11, s10, 31
	v_cvt_pk_bf16_f32 v134, v70, v71
	v_cvt_pk_bf16_f32 v135, v72, v73
	v_cvt_pk_bf16_f32 v136, v66, v67
	v_cvt_pk_bf16_f32 v137, v68, v69
	v_cvt_pk_bf16_f32 v142, v62, v63
	v_cvt_pk_bf16_f32 v143, v64, v65
	v_cvt_pk_bf16_f32 v144, v58, v59
	v_cvt_pk_bf16_f32 v145, v60, v61
	v_cvt_pk_bf16_f32 v146, v54, v55
	v_cvt_pk_bf16_f32 v147, v56, v57
	v_cvt_pk_bf16_f32 v148, v50, v51
	v_cvt_pk_bf16_f32 v149, v52, v53
	v_cvt_pk_bf16_f32 v150, v46, v47
	v_cvt_pk_bf16_f32 v151, v48, v49
	v_cvt_pk_bf16_f32 v152, v42, v43
	v_cvt_pk_bf16_f32 v153, v44, v45
	v_cvt_pk_bf16_f32 v154, v38, v39
	v_cvt_pk_bf16_f32 v155, v40, v41
	v_cvt_pk_bf16_f32 v156, v34, v35
	v_cvt_pk_bf16_f32 v157, v32, v33
	v_cvt_pk_bf16_f32 v158, v30, v31
	v_cvt_pk_bf16_f32 v159, v36, v37
	v_cvt_pk_bf16_f32 v160, v78, v81
	v_cvt_pk_bf16_f32 v161, v74, v77
	v_cvt_pk_bf16_f32 v138, v26, v27
	v_cvt_pk_bf16_f32 v139, v28, v29
	v_cvt_pk_bf16_f32 v140, v22, v23
	v_cvt_pk_bf16_f32 v141, v24, v25
	v_cvt_pk_bf16_f32 v130, v18, v19
	v_cvt_pk_bf16_f32 v131, v20, v21
	v_cvt_pk_bf16_f32 v132, v6, v7
	v_cvt_pk_bf16_f32 v133, v2, v3
	v_lshl_add_u64 v[2:3], s[10:11], 0, v[184:185]
	v_mov_b64_e32 v[4:5], s[12:13]
	v_mad_u64_u32 v[6:7], s[24:25], v2, s65, v[4:5]
	v_mad_i32_i24 v7, v3, s65, v7
	v_mov_b32_e32 v195, v1
	v_lshl_add_u64 v[10:11], v[6:7], 0, v[194:195]
	v_lshl_add_u64 v[6:7], v[186:187], 0, s[10:11]
	v_mad_u64_u32 v[4:5], s[24:25], v6, s65, v[4:5]
	v_mad_i32_i24 v5, v7, s65, v5
	v_lshl_add_u64 v[14:15], v[4:5], 0, v[194:195]
	v_mov_b64_e32 v[4:5], s[14:15]
	v_mad_u64_u32 v[8:9], s[24:25], v2, s65, v[4:5]
	v_mad_u64_u32 v[4:5], s[24:25], v6, s65, v[4:5]
	v_mad_i32_i24 v9, v3, s65, v9
	v_mad_i32_i24 v5, v7, s65, v5
	v_lshl_add_u64 v[2:3], v[8:9], 0, v[194:195]
	v_lshl_add_u64 v[6:7], v[4:5], 0, v[194:195]
	global_load_dwordx4 v[2:5], v[2:3], off
	s_nop 0
	global_load_dwordx4 v[6:9], v[6:7], off
	s_nop 0
	global_load_dwordx4 v[10:13], v[10:11], off
	s_nop 0
	global_load_dwordx4 v[14:17], v[14:15], off
	v_lshl_add_u64 v[198:199], s[12:13], 0, v[194:195]
	s_or_b32 s12, s10, 64
	s_ashr_i32 s13, s12, 31
	v_add_u32_e32 v62, 16, v222
	v_lshl_add_u64 v[200:201], s[14:15], 0, v[194:195]
	v_lshl_add_u64 v[18:19], s[12:13], 0, v[184:185]
	v_add_u32_e32 v63, 16, v223
	v_add_u32_e32 v64, 16, v224
	v_add_u32_e32 v67, 16, v225
	v_lshl_add_u64 v[20:21], v[186:187], 0, s[12:13]
	v_mad_u64_u32 v[22:23], s[12:13], v18, s65, v[198:199]
	s_waitcnt vmcnt(0)
	v_mad_u64_u32 v[24:25], s[12:13], v20, s65, v[198:199]
	v_mad_i32_i24 v23, v19, s65, v23
	v_mad_i32_i24 v25, v21, s65, v25
	s_waitcnt vmcnt(3)
	ds_write_b128 v62, v[2:5]
	s_waitcnt vmcnt(2)
	ds_write_b128 v63, v[6:9]
	s_waitcnt vmcnt(1)
	ds_write_b128 v64, v[10:13] offset:32768
	s_waitcnt vmcnt(0)
	ds_write_b128 v67, v[14:17] offset:32768
	v_mad_u64_u32 v[2:3], s[12:13], v18, s65, v[200:201]
	v_mad_i32_i24 v3, v19, s65, v3
	v_mad_u64_u32 v[4:5], s[12:13], v20, s65, v[200:201]
	s_waitcnt lgkmcnt(0)
	s_barrier
	global_load_dwordx4 v[50:53], v[22:23], off
	global_load_dwordx4 v[68:71], v[24:25], off
	v_mad_i32_i24 v5, v21, s65, v5
	global_load_dwordx4 v[54:57], v[2:3], off
	global_load_dwordx4 v[58:61], v[4:5], off
	v_add_u32_e32 v6, v227, v228
	ds_read_b128 v[2:5], v6 offset:32768
	ds_read_b128 v[18:21], v6 offset:40960
	v_add_u32_e32 v38, v227, v229
	ds_read_b128 v[34:37], v38 offset:32768
	ds_read_b128 v[38:41], v38 offset:40960
	s_waitcnt lgkmcnt(3)
	v_mfma_f32_32x32x16_bf16 v[2:17], v[2:5], v[134:137], 0
	s_waitcnt lgkmcnt(2)
	v_mfma_f32_32x32x16_bf16 v[18:33], v[18:21], v[134:137], 0
	s_waitcnt lgkmcnt(1)
	v_mfma_f32_32x32x16_bf16 v[2:17], v[34:37], v[142:145], v[2:17]
	s_waitcnt lgkmcnt(0)
	v_mfma_f32_32x32x16_bf16 v[18:33], v[38:41], v[142:145], v[18:33]
	v_add_u32_e32 v38, v227, v230
	ds_read_b128 v[34:37], v38 offset:32768
	ds_read_b128 v[38:41], v38 offset:40960
	s_waitcnt lgkmcnt(1)
	v_mfma_f32_32x32x16_bf16 v[2:17], v[34:37], v[146:149], v[2:17]
	s_waitcnt lgkmcnt(0)
	v_mfma_f32_32x32x16_bf16 v[18:33], v[38:41], v[146:149], v[18:33]
	v_add_u32_e32 v38, v227, v231
	ds_read_b128 v[34:37], v38 offset:32768
	ds_read_b128 v[38:41], v38 offset:40960
	s_waitcnt lgkmcnt(1)
	v_mfma_f32_32x32x16_bf16 v[2:17], v[34:37], v[150:153], v[2:17]
	s_waitcnt lgkmcnt(0)
	v_mfma_f32_32x32x16_bf16 v[18:33], v[38:41], v[150:153], v[18:33]
	v_add_u32_e32 v38, v227, v232
	ds_read_b128 v[34:37], v38 offset:32768
	ds_read_b128 v[38:41], v38 offset:40960
	s_waitcnt lgkmcnt(1)
	v_mfma_f32_32x32x16_bf16 v[2:17], v[34:37], v[154:157], v[2:17]
	s_waitcnt lgkmcnt(0)
	v_mfma_f32_32x32x16_bf16 v[18:33], v[38:41], v[154:157], v[18:33]
	v_add_u32_e32 v38, v227, v233
	ds_read_b128 v[34:37], v38 offset:32768
	ds_read_b128 v[38:41], v38 offset:40960
	s_waitcnt lgkmcnt(1)
	v_mfma_f32_32x32x16_bf16 v[2:17], v[34:37], v[158:161], v[2:17]
	s_waitcnt lgkmcnt(0)
	v_mfma_f32_32x32x16_bf16 v[18:33], v[38:41], v[158:161], v[18:33]
	v_add_u32_e32 v38, v227, v234
	ds_read_b128 v[34:37], v38 offset:32768
	ds_read_b128 v[38:41], v38 offset:40960
	s_waitcnt lgkmcnt(1)
	v_mfma_f32_32x32x16_bf16 v[2:17], v[34:37], v[138:141], v[2:17]
	s_waitcnt lgkmcnt(0)
	v_mfma_f32_32x32x16_bf16 v[18:33], v[38:41], v[138:141], v[18:33]
	v_add_u32_e32 v38, v227, v235
	ds_read_b128 v[34:37], v38 offset:32768
	ds_read_b128 v[38:41], v38 offset:40960
	s_waitcnt lgkmcnt(1)
	v_mfma_f32_32x32x16_bf16 v[2:17], v[34:37], v[130:133], v[2:17]
	s_waitcnt lgkmcnt(0)
	v_mfma_f32_32x32x16_bf16 v[18:33], v[38:41], v[130:133], v[18:33]
	s_nop 9
	v_max_f32_e32 v34, v3, v3
	v_max_f32_e32 v35, v2, v2
	v_max_f32_e32 v34, v35, v34
	v_max3_f32 v34, v34, v4, v5
	v_max3_f32 v34, v34, v6, v7
	v_max3_f32 v34, v34, v8, v9
	v_max3_f32 v34, v34, v10, v11
	v_max3_f32 v34, v34, v12, v13
	v_max3_f32 v34, v34, v14, v15
	v_max3_f32 v34, v34, v16, v17
	v_max3_f32 v34, v34, v18, v19
	v_max3_f32 v34, v34, v20, v21
	v_max3_f32 v34, v34, v22, v23
	v_max3_f32 v34, v34, v24, v25
	v_max3_f32 v34, v34, v26, v27
	v_max3_f32 v34, v34, v28, v29
	v_max3_f32 v34, v34, v30, v31
	v_max3_f32 v34, v34, v32, v33
	v_mov_b32_e32 v35, v34
	s_nop 1
	v_permlane32_swap_b32_e32 v34, v35
	v_max_f32_e32 v35, v35, v35
	v_max_f32_e32 v34, v34, v34
	v_max_f32_e32 v35, v34, v35
	v_sub_f32_e32 v2, v2, v35
	v_sub_f32_e32 v3, v3, v35
	v_exp_f32_e32 v2, v2
	v_sub_f32_e32 v4, v4, v35
	v_exp_f32_e32 v3, v3
	v_sub_f32_e32 v5, v5, v35
	v_exp_f32_e32 v4, v4
	v_sub_f32_e32 v6, v6, v35
	v_exp_f32_e32 v5, v5
	v_sub_f32_e32 v7, v7, v35
	v_exp_f32_e32 v6, v6
	v_add_f32_e32 v34, 0, v2
	v_sub_f32_e32 v8, v8, v35
	v_exp_f32_e32 v7, v7
	v_add_f32_e32 v34, v3, v34
	v_sub_f32_e32 v9, v9, v35
	v_exp_f32_e32 v8, v8
	v_add_f32_e32 v34, v4, v34
	v_sub_f32_e32 v10, v10, v35
	v_exp_f32_e32 v9, v9
	v_add_f32_e32 v34, v5, v34
	v_sub_f32_e32 v11, v11, v35
	v_exp_f32_e32 v10, v10
	v_add_f32_e32 v34, v6, v34
	v_sub_f32_e32 v12, v12, v35
	v_exp_f32_e32 v11, v11
	v_add_f32_e32 v34, v7, v34
	v_sub_f32_e32 v13, v13, v35
	v_exp_f32_e32 v12, v12
	v_add_f32_e32 v34, v8, v34
	v_sub_f32_e32 v14, v14, v35
	v_exp_f32_e32 v13, v13
	v_add_f32_e32 v34, v9, v34
	v_sub_f32_e32 v15, v15, v35
	v_exp_f32_e32 v14, v14
	v_add_f32_e32 v34, v10, v34
	v_sub_f32_e32 v16, v16, v35
	v_exp_f32_e32 v15, v15
	v_add_f32_e32 v34, v11, v34
	v_sub_f32_e32 v17, v17, v35
	v_exp_f32_e32 v16, v16
	v_add_f32_e32 v34, v12, v34
	v_sub_f32_e32 v18, v18, v35
	v_exp_f32_e32 v17, v17
	v_add_f32_e32 v34, v13, v34
	v_sub_f32_e32 v19, v19, v35
	v_exp_f32_e32 v18, v18
	v_add_f32_e32 v34, v14, v34
	v_sub_f32_e32 v20, v20, v35
	v_exp_f32_e32 v19, v19
	v_add_f32_e32 v34, v15, v34
	v_sub_f32_e32 v21, v21, v35
	v_exp_f32_e32 v20, v20
	v_add_f32_e32 v34, v16, v34
	v_sub_f32_e32 v22, v22, v35
	v_exp_f32_e32 v21, v21
	v_add_f32_e32 v34, v17, v34
	v_sub_f32_e32 v23, v23, v35
	v_exp_f32_e32 v22, v22
	v_add_f32_e32 v34, v18, v34
	v_sub_f32_e32 v24, v24, v35
	v_exp_f32_e32 v23, v23
	v_add_f32_e32 v34, v19, v34
	v_sub_f32_e32 v25, v25, v35
	v_exp_f32_e32 v24, v24
	v_add_f32_e32 v34, v20, v34
	v_sub_f32_e32 v26, v26, v35
	v_exp_f32_e32 v25, v25
	v_add_f32_e32 v34, v21, v34
	v_sub_f32_e32 v27, v27, v35
	v_exp_f32_e32 v26, v26
	v_add_f32_e32 v34, v22, v34
	v_sub_f32_e32 v28, v28, v35
	v_exp_f32_e32 v27, v27
	v_add_f32_e32 v34, v23, v34
	v_sub_f32_e32 v29, v29, v35
	v_exp_f32_e32 v28, v28
	v_add_f32_e32 v34, v24, v34
	v_sub_f32_e32 v30, v30, v35
	v_exp_f32_e32 v29, v29
	v_add_f32_e32 v34, v25, v34
	v_sub_f32_e32 v31, v31, v35
	v_exp_f32_e32 v30, v30
	v_add_f32_e32 v34, v26, v34
	v_sub_f32_e32 v32, v32, v35
	v_exp_f32_e32 v31, v31
	v_add_f32_e32 v34, v27, v34
	v_sub_f32_e32 v33, v33, v35
	v_exp_f32_e32 v32, v32
	v_add_f32_e32 v34, v28, v34
	v_exp_f32_e32 v33, v33
	v_add_f32_e32 v34, v29, v34
	v_add_f32_e32 v34, v30, v34
	v_add_f32_e32 v34, v31, v34
	v_add_f32_e32 v34, v32, v34
	v_add_f32_e32 v34, v33, v34
	v_mov_b32_e32 v36, v34
	s_nop 1
	v_permlane32_swap_b32_e32 v34, v36
	v_add_f32_e32 v34, v34, v36
	v_pk_add_f32 v[202:203], v[34:35], 0 op_sel_hi:[1,0]
	v_cvt_pk_bf16_f32 v72, v2, v3
	v_cvt_pk_bf16_f32 v73, v4, v5
	v_cvt_pk_bf16_f32 v74, v6, v7
	v_cvt_pk_bf16_f32 v75, v8, v9
	v_cvt_pk_bf16_f32 v76, v10, v11
	s_nop 0
	v_xor_b32_e32 v66, 0x80000000, v203
	v_cvt_pk_bf16_f32 v77, v12, v13
	v_cvt_pk_bf16_f32 v78, v14, v15
	v_cvt_pk_bf16_f32 v79, v16, v17
	v_cvt_pk_bf16_f32 v80, v18, v19
	v_cvt_pk_bf16_f32 v81, v20, v21
	v_cvt_pk_bf16_f32 v82, v22, v23
	v_cvt_pk_bf16_f32 v83, v24, v25
	v_cvt_pk_bf16_f32 v84, v26, v27
	v_cvt_pk_bf16_f32 v85, v28, v29
	v_cvt_pk_bf16_f32 v86, v30, v31
	v_cvt_pk_bf16_f32 v87, v32, v33
	ds_read_b64_tr_b16 v[2:3], v237 offset:0
	ds_read_b64_tr_b16 v[4:5], v237 offset:0x800
	ds_read_b64_tr_b16 v[18:19], v237 offset:0x1000
	ds_read_b64_tr_b16 v[20:21], v237 offset:0x1800
	ds_read_b64_tr_b16 v[22:23], v237 offset:0x2000
	ds_read_b64_tr_b16 v[24:25], v237 offset:0x2800
	ds_read_b64_tr_b16 v[26:27], v237 offset:0x3000
	ds_read_b64_tr_b16 v[28:29], v237 offset:0x3800
	s_waitcnt lgkmcnt(0)
	s_nop 0
	v_mfma_f32_32x32x16_bf16 v[2:17], v[72:75], v[2:5], 0
	v_mfma_f32_32x32x16_bf16 v[2:17], v[76:79], v[18:21], v[2:17]
	ds_read_b64_tr_b16 v[18:19], v237 offset:0x200
	ds_read_b64_tr_b16 v[20:21], v237 offset:0xa00
	ds_read_b64_tr_b16 v[34:35], v237 offset:0x1200
	ds_read_b64_tr_b16 v[36:37], v237 offset:0x1a00
	ds_read_b64_tr_b16 v[38:39], v237 offset:0x2200
	ds_read_b64_tr_b16 v[40:41], v237 offset:0x2a00
	ds_read_b64_tr_b16 v[42:43], v237 offset:0x3200
	v_mfma_f32_32x32x16_bf16 v[2:17], v[80:83], v[22:25], v[2:17]
	ds_read_b64_tr_b16 v[44:45], v237 offset:0x3a00
	s_waitcnt lgkmcnt(0)
	v_mfma_f32_32x32x16_bf16 v[2:17], v[84:87], v[26:29], v[2:17]
	v_mfma_f32_32x32x16_bf16 v[18:33], v[72:75], v[18:21], 0
	v_mfma_f32_32x32x16_bf16 v[18:33], v[76:79], v[34:37], v[18:33]
	ds_read_b64_tr_b16 v[34:35], v237 offset:0x400
	ds_read_b64_tr_b16 v[36:37], v237 offset:0xc00
	ds_read_b64_tr_b16 v[88:89], v237 offset:0x1400
	ds_read_b64_tr_b16 v[90:91], v237 offset:0x1c00
	ds_read_b64_tr_b16 v[92:93], v237 offset:0x2400
	ds_read_b64_tr_b16 v[94:95], v237 offset:0x2c00
	ds_read_b64_tr_b16 v[96:97], v237 offset:0x3400
	v_mfma_f32_32x32x16_bf16 v[18:33], v[80:83], v[38:41], v[18:33]
	ds_read_b64_tr_b16 v[98:99], v237 offset:0x3c00
	s_waitcnt lgkmcnt(0)
	v_mfma_f32_32x32x16_bf16 v[18:33], v[84:87], v[42:45], v[18:33]
	v_mfma_f32_32x32x16_bf16 v[34:49], v[72:75], v[34:37], 0
	v_mfma_f32_32x32x16_bf16 v[34:49], v[76:79], v[88:91], v[34:49]
	ds_read_b64_tr_b16 v[88:89], v237 offset:0x600
	ds_read_b64_tr_b16 v[90:91], v237 offset:0xe00
	v_mfma_f32_32x32x16_bf16 v[34:49], v[80:83], v[92:95], v[34:49]
	ds_read_b64_tr_b16 v[92:93], v237 offset:0x1600
	ds_read_b64_tr_b16 v[94:95], v237 offset:0x1e00
	v_mfma_f32_32x32x16_bf16 v[34:49], v[84:87], v[96:99], v[34:49]
	ds_read_b64_tr_b16 v[96:97], v237 offset:0x2600
	ds_read_b64_tr_b16 v[98:99], v237 offset:0x2e00
	ds_read_b64_tr_b16 v[100:101], v237 offset:0x3600
	ds_read_b64_tr_b16 v[102:103], v237 offset:0x3e00
	s_waitcnt lgkmcnt(0)
	s_waitcnt vmcnt(1)
	ds_write_b128 v62, v[54:57] offset:16384
	s_waitcnt vmcnt(0)
	ds_write_b128 v63, v[58:61] offset:16384
	ds_write_b128 v64, v[50:53] offset:49152
	v_mfma_f32_32x32x16_bf16 v[50:65], v[72:75], v[88:91], 0
	ds_write_b128 v67, v[68:71] offset:49152
	s_addk_i32 s10, 0x80
	s_mov_b32 s14, 0
	s_movk_i32 s15, 0x4000
	v_mov_b32_e32 v67, v66
	v_mov_b32_e32 v68, v66
	v_mov_b32_e32 v69, v66
	v_mfma_f32_32x32x16_bf16 v[50:65], v[76:79], v[92:95], v[50:65]
	v_mov_b32_e32 v70, v66
	v_mov_b32_e32 v71, v66
	v_mov_b32_e32 v72, v66
	v_mov_b32_e32 v73, v66
	v_mov_b32_e32 v74, v66
	v_mov_b32_e32 v75, v66
	v_mov_b32_e32 v76, v66
	v_mfma_f32_32x32x16_bf16 v[50:65], v[80:83], v[96:99], v[50:65]
	v_mov_b32_e32 v77, v66
	v_mov_b32_e32 v78, v66
	v_mov_b32_e32 v79, v66
	v_mov_b32_e32 v80, v66
	v_mov_b32_e32 v81, v66
	s_waitcnt lgkmcnt(0)
	s_barrier
	v_mfma_f32_32x32x16_bf16 v[50:65], v[84:87], v[100:103], v[50:65]
	s_and_b32 s24, s22, 7
	s_lshl_b32 s24, s24, 6
	s_and_b32 s24, s24, 0x100
	s_mul_i32 s25, s10, 0x1400
	s_add_u32 s24, s24, s25
	s_add_u32 s24, s18, s24
	s_addc_u32 s25, s19, 0
	v_readlane_b32 s26, v254, 10
	s_nop 3
	s_lshl_b32 s26, s26, 5
	s_add_i32 s26, s26, 16
	v_add_u32_e32 v162, v227, v228
	v_add_u32_e32 v163, v227, v229
	v_add_u32_e32 v164, v227, v230
	v_add_u32_e32 v165, v227, v231
	v_add_u32_e32 v166, v227, v232
	v_add_u32_e32 v167, v227, v233
	v_add_u32_e32 v168, v227, v234
	v_add_u32_e32 v169, v227, v235
	s_nop 0
	s_nop 0
	s_nop 0
	s_add_i32 m0, s26, 0x8000
	s_nop 0
	global_load_lds_dwordx4 v252, s[24:25]
	s_add_i32 m0, s26, 0x8400
	s_nop 0
	global_load_lds_dwordx4 v253, s[24:25]
	s_add_u32 s24, s24, 0x50000
	s_addc_u32 s25, s25, 0
.Lgu_a286:
	ds_read_b128 v[82:85], v162 offset:49152
	ds_read_b128 v[86:89], v162 offset:57344
	ds_read_b128 v[90:93], v163 offset:49152
	ds_read_b128 v[94:97], v163 offset:57344
	s_waitcnt lgkmcnt(3)
	v_mfma_f32_32x32x16_bf16 v[114:129], v[82:85], v[134:137], v[66:81]
	s_waitcnt lgkmcnt(2)
	v_mfma_f32_32x32x16_bf16 v[98:113], v[86:89], v[134:137], v[66:81]
	ds_read_b128 v[82:85], v164 offset:49152
	ds_read_b128 v[86:89], v164 offset:57344
	s_waitcnt lgkmcnt(3)
	v_mfma_f32_32x32x16_bf16 v[114:129], v[90:93], v[142:145], v[114:129]
	s_waitcnt lgkmcnt(2)
	v_mfma_f32_32x32x16_bf16 v[98:113], v[94:97], v[142:145], v[98:113]
	ds_read_b128 v[90:93], v165 offset:49152
	ds_read_b128 v[94:97], v165 offset:57344
	s_waitcnt lgkmcnt(3)
	v_mfma_f32_32x32x16_bf16 v[114:129], v[82:85], v[146:149], v[114:129]
	s_waitcnt lgkmcnt(2)
	v_mfma_f32_32x32x16_bf16 v[98:113], v[86:89], v[146:149], v[98:113]
	ds_read_b128 v[82:85], v166 offset:49152
	ds_read_b128 v[86:89], v166 offset:57344
	s_waitcnt lgkmcnt(3)
	v_mfma_f32_32x32x16_bf16 v[114:129], v[90:93], v[150:153], v[114:129]
	s_waitcnt lgkmcnt(2)
	v_mfma_f32_32x32x16_bf16 v[98:113], v[94:97], v[150:153], v[98:113]
	ds_read_b128 v[90:93], v167 offset:49152
	ds_read_b128 v[94:97], v167 offset:57344
	s_waitcnt lgkmcnt(3)
	v_mfma_f32_32x32x16_bf16 v[114:129], v[82:85], v[154:157], v[114:129]
	s_waitcnt lgkmcnt(2)
	v_mfma_f32_32x32x16_bf16 v[98:113], v[86:89], v[154:157], v[98:113]
	ds_read_b128 v[82:85], v168 offset:49152
	ds_read_b128 v[86:89], v168 offset:57344
	s_waitcnt lgkmcnt(3)
	v_mfma_f32_32x32x16_bf16 v[114:129], v[90:93], v[158:161], v[114:129]
	s_waitcnt lgkmcnt(2)
	v_mfma_f32_32x32x16_bf16 v[98:113], v[94:97], v[158:161], v[98:113]
	ds_read_b128 v[90:93], v169 offset:49152
	ds_read_b128 v[94:97], v169 offset:57344
	s_waitcnt lgkmcnt(3)
	v_mfma_f32_32x32x16_bf16 v[114:129], v[82:85], v[138:141], v[114:129]
	s_waitcnt lgkmcnt(2)
	v_mfma_f32_32x32x16_bf16 v[98:113], v[86:89], v[138:141], v[98:113]
	s_waitcnt lgkmcnt(1)
	v_mfma_f32_32x32x16_bf16 v[114:129], v[90:93], v[130:133], v[114:129]
	s_waitcnt lgkmcnt(0)
	v_mfma_f32_32x32x16_bf16 v[98:113], v[94:97], v[130:133], v[98:113]
	s_cmpk_ge_u32 s26, 0x2010
	s_cbranch_scc0 .Lpp_a_sA
	s_waitcnt vmcnt(0)
	s_barrier
	s_nop 0
	s_nop 0
	s_nop 0
	s_nop 0
	s_sub_u32 s36, s24, 0x50000
	s_subb_u32 s37, s25, 0
	s_add_i32 m0, s26, 0x0
	s_nop 0
	global_load_lds_dwordx4 v250, s[36:37]
	s_add_i32 m0, s26, 0x400
	s_nop 0
	global_load_lds_dwordx4 v251, s[36:37]
	s_add_i32 s38, s14, 1
	s_cmp_eq_u32 s38, s23
	s_cbranch_scc1 .Lpp_a_s_nok
	s_add_i32 m0, s26, 0xc000
	s_nop 0
	global_load_lds_dwordx4 v252, s[24:25]
	s_add_i32 m0, s26, 0xc400
	s_nop 0
	global_load_lds_dwordx4 v253, s[24:25]
	s_add_u32 s24, s24, 0x50000
	s_addc_u32 s25, s25, 0
.Lpp_a_s_nok:
	s_branch .Lpp_a_sJ
.Lpp_a_sA:
	s_nop 11
.Lpp_a_sJ:
	s_nop 1
	v_max_f32_e32 v82, v115, v115
	v_max_f32_e32 v83, v114, v114
	v_max_f32_e32 v82, v83, v82
	v_max3_f32 v82, v82, v116, v117
	v_max3_f32 v82, v82, v118, v119
	v_max3_f32 v82, v82, v120, v121
	v_max3_f32 v82, v82, v122, v123
	v_max3_f32 v82, v82, v124, v125
	v_max3_f32 v82, v82, v126, v127
	v_max3_f32 v82, v82, v128, v129
	v_max3_f32 v82, v82, v98, v99
	v_max3_f32 v82, v82, v100, v101
	v_max3_f32 v82, v82, v102, v103
	v_max3_f32 v82, v82, v104, v105
	v_max3_f32 v82, v82, v106, v107
	v_max3_f32 v82, v82, v108, v109
	v_max3_f32 v82, v82, v110, v111
	v_max3_f32 v82, v82, v112, v113
	v_mov_b32_e32 v83, v82
	s_nop 1
	v_permlane32_swap_b32_e32 v82, v83
	v_max_f32_e32 v83, v83, v83
	v_max_f32_e32 v82, v82, v82
	v_max_f32_e32 v82, v82, v83
	v_cmp_ge_f32_e32 vcc, s64, v82
	s_cmp_eq_u64 vcc, exec
	s_cbranch_scc0 .Lgu_a294
	v_mov_b32_e32 v195, 1.0

.Lgu_a292:
	v_add_f32_e32 v114, v114, v115
	v_fmac_f32_e32 v114, v202, v195
	s_cmpk_ge_u32 s26, 0x2010
	s_cbranch_scc1 .Lpp_a_pJ
	s_waitcnt vmcnt(0)
	s_barrier
	s_nop 0
	s_nop 0
	s_sub_u32 s36, s24, 0x50000
	s_subb_u32 s37, s25, 0
	s_add_i32 m0, s26, 0x0
	s_nop 0
	global_load_lds_dwordx4 v250, s[36:37]
	s_add_i32 m0, s26, 0x400
	s_nop 0
	global_load_lds_dwordx4 v251, s[36:37]
	s_add_i32 s38, s14, 1
	s_cmp_eq_u32 s38, s23
	s_cbranch_scc1 .Lpp_a_p_nok
	s_add_i32 m0, s26, 0xc000
	s_nop 0
	global_load_lds_dwordx4 v252, s[24:25]
	s_add_i32 m0, s26, 0xc400
	s_nop 0
	global_load_lds_dwordx4 v253, s[24:25]
	s_add_u32 s24, s24, 0x50000
	s_addc_u32 s25, s25, 0
.Lpp_a_p_nok:
.Lpp_a_pJ:
	ds_read_b64_tr_b16 v[116:117], v237 offset:16384
	ds_read_b64_tr_b16 v[118:119], v237 offset:18432
	ds_read_b64_tr_b16 v[120:121], v237 offset:20480
	ds_read_b64_tr_b16 v[122:123], v237 offset:22528
	ds_read_b64_tr_b16 v[124:125], v237 offset:24576
	ds_read_b64_tr_b16 v[126:127], v237 offset:26624
	ds_read_b64_tr_b16 v[238:239], v237 offset:28672
	ds_read_b64_tr_b16 v[240:241], v237 offset:30720
	s_nop 0
	s_waitcnt lgkmcnt(6)
	v_mfma_f32_32x32x16_bf16 v[2:17], v[110:113], v[116:119], v[2:17]
	ds_read_b64_tr_b16 v[116:117], v237 offset:16896
	ds_read_b64_tr_b16 v[118:119], v237 offset:18944
	s_waitcnt lgkmcnt(6)
	v_mfma_f32_32x32x16_bf16 v[2:17], v[106:109], v[120:123], v[2:17]
	ds_read_b64_tr_b16 v[120:121], v237 offset:20992
	ds_read_b64_tr_b16 v[122:123], v237 offset:23040
	s_waitcnt lgkmcnt(6)
	v_mfma_f32_32x32x16_bf16 v[2:17], v[102:105], v[124:127], v[2:17]
	ds_read_b64_tr_b16 v[124:125], v237 offset:25088
	ds_read_b64_tr_b16 v[126:127], v237 offset:27136
	s_waitcnt lgkmcnt(6)
	v_mfma_f32_32x32x16_bf16 v[2:17], v[98:101], v[238:241], v[2:17]
	ds_read_b64_tr_b16 v[238:239], v237 offset:29184
	ds_read_b64_tr_b16 v[240:241], v237 offset:31232
	s_waitcnt lgkmcnt(6)
	v_mfma_f32_32x32x16_bf16 v[18:33], v[110:113], v[116:119], v[18:33]
	ds_read_b64_tr_b16 v[116:117], v237 offset:17408
	ds_read_b64_tr_b16 v[118:119], v237 offset:19456
	s_waitcnt lgkmcnt(6)
	v_mfma_f32_32x32x16_bf16 v[18:33], v[106:109], v[120:123], v[18:33]
	ds_read_b64_tr_b16 v[120:121], v237 offset:21504
	ds_read_b64_tr_b16 v[122:123], v237 offset:23552
	s_waitcnt lgkmcnt(6)
	v_mfma_f32_32x32x16_bf16 v[18:33], v[102:105], v[124:127], v[18:33]
	ds_read_b64_tr_b16 v[124:125], v237 offset:25600
	ds_read_b64_tr_b16 v[126:127], v237 offset:27648
	s_waitcnt lgkmcnt(6)
	v_mfma_f32_32x32x16_bf16 v[18:33], v[98:101], v[238:241], v[18:33]
	ds_read_b64_tr_b16 v[238:239], v237 offset:29696
	ds_read_b64_tr_b16 v[240:241], v237 offset:31744
	s_waitcnt lgkmcnt(6)
	v_mfma_f32_32x32x16_bf16 v[34:49], v[110:113], v[116:119], v[34:49]
	ds_read_b64_tr_b16 v[116:117], v237 offset:17920
	ds_read_b64_tr_b16 v[118:119], v237 offset:19968
	s_waitcnt lgkmcnt(6)
	v_mfma_f32_32x32x16_bf16 v[34:49], v[106:109], v[120:123], v[34:49]
	ds_read_b64_tr_b16 v[120:121], v237 offset:22016
	ds_read_b64_tr_b16 v[122:123], v237 offset:24064
	s_waitcnt lgkmcnt(6)
	v_mfma_f32_32x32x16_bf16 v[34:49], v[102:105], v[124:127], v[34:49]
	ds_read_b64_tr_b16 v[124:125], v237 offset:26112
	ds_read_b64_tr_b16 v[126:127], v237 offset:28160
	s_waitcnt lgkmcnt(6)
	v_mfma_f32_32x32x16_bf16 v[34:49], v[98:101], v[238:241], v[34:49]
	ds_read_b64_tr_b16 v[238:239], v237 offset:30208
	ds_read_b64_tr_b16 v[240:241], v237 offset:32256
	s_waitcnt lgkmcnt(6)
	v_mfma_f32_32x32x16_bf16 v[50:65], v[110:113], v[116:119], v[50:65]
	s_add_i32 s14, s14, 1
	s_cmp_eq_u32 s23, s14
	s_waitcnt lgkmcnt(4)
	v_mfma_f32_32x32x16_bf16 v[50:65], v[106:109], v[120:123], v[50:65]
	s_waitcnt lgkmcnt(2)
	v_mfma_f32_32x32x16_bf16 v[50:65], v[102:105], v[124:127], v[50:65]
	s_waitcnt lgkmcnt(0)
	v_mfma_f32_32x32x16_bf16 v[50:65], v[98:101], v[238:241], v[50:65]
	v_mov_b32_e32 v202, v114
.Lgu_b286:
	ds_read_b128 v[82:85], v162 offset:32768
	ds_read_b128 v[86:89], v162 offset:40960
	ds_read_b128 v[90:93], v163 offset:32768
	ds_read_b128 v[94:97], v163 offset:40960
	s_waitcnt lgkmcnt(3)
	v_mfma_f32_32x32x16_bf16 v[114:129], v[82:85], v[134:137], v[66:81]
	s_waitcnt lgkmcnt(2)
	v_mfma_f32_32x32x16_bf16 v[98:113], v[86:89], v[134:137], v[66:81]
	ds_read_b128 v[82:85], v164 offset:32768
	ds_read_b128 v[86:89], v164 offset:40960
	s_waitcnt lgkmcnt(3)
	v_mfma_f32_32x32x16_bf16 v[114:129], v[90:93], v[142:145], v[114:129]
	s_waitcnt lgkmcnt(2)
	v_mfma_f32_32x32x16_bf16 v[98:113], v[94:97], v[142:145], v[98:113]
	ds_read_b128 v[90:93], v165 offset:32768
	ds_read_b128 v[94:97], v165 offset:40960
	s_waitcnt lgkmcnt(3)
	v_mfma_f32_32x32x16_bf16 v[114:129], v[82:85], v[146:149], v[114:129]
	s_waitcnt lgkmcnt(2)
	v_mfma_f32_32x32x16_bf16 v[98:113], v[86:89], v[146:149], v[98:113]
	ds_read_b128 v[82:85], v166 offset:32768
	ds_read_b128 v[86:89], v166 offset:40960
	s_waitcnt lgkmcnt(3)
	v_mfma_f32_32x32x16_bf16 v[114:129], v[90:93], v[150:153], v[114:129]
	s_waitcnt lgkmcnt(2)
	v_mfma_f32_32x32x16_bf16 v[98:113], v[94:97], v[150:153], v[98:113]
	ds_read_b128 v[90:93], v167 offset:32768
	ds_read_b128 v[94:97], v167 offset:40960
	s_waitcnt lgkmcnt(3)
	v_mfma_f32_32x32x16_bf16 v[114:129], v[82:85], v[154:157], v[114:129]
	s_waitcnt lgkmcnt(2)
	v_mfma_f32_32x32x16_bf16 v[98:113], v[86:89], v[154:157], v[98:113]
	ds_read_b128 v[82:85], v168 offset:32768
	ds_read_b128 v[86:89], v168 offset:40960
	s_waitcnt lgkmcnt(3)
	v_mfma_f32_32x32x16_bf16 v[114:129], v[90:93], v[158:161], v[114:129]
	s_waitcnt lgkmcnt(2)
	v_mfma_f32_32x32x16_bf16 v[98:113], v[94:97], v[158:161], v[98:113]
	ds_read_b128 v[90:93], v169 offset:32768
	ds_read_b128 v[94:97], v169 offset:40960
	s_waitcnt lgkmcnt(3)
	v_mfma_f32_32x32x16_bf16 v[114:129], v[82:85], v[138:141], v[114:129]
	s_waitcnt lgkmcnt(2)
	v_mfma_f32_32x32x16_bf16 v[98:113], v[86:89], v[138:141], v[98:113]
	s_waitcnt lgkmcnt(1)
	v_mfma_f32_32x32x16_bf16 v[114:129], v[90:93], v[130:133], v[114:129]
	s_waitcnt lgkmcnt(0)
	v_mfma_f32_32x32x16_bf16 v[98:113], v[94:97], v[130:133], v[98:113]
	s_cmpk_ge_u32 s26, 0x2010
	s_cbranch_scc0 .Lpp_b_sA
	s_waitcnt vmcnt(0)
	s_barrier
	s_nop 0
	s_nop 0
	s_nop 0
	s_nop 0
	s_sub_u32 s36, s24, 0x50000
	s_subb_u32 s37, s25, 0
	s_add_i32 m0, s26, 0x4000
	s_nop 0
	global_load_lds_dwordx4 v250, s[36:37]
	s_add_i32 m0, s26, 0x4400
	s_nop 0
	global_load_lds_dwordx4 v251, s[36:37]
	s_add_i32 s38, s14, 1
	s_cmp_eq_u32 s38, s23
	s_cbranch_scc1 .Lpp_b_s_nok
	s_add_i32 m0, s26, 0x8000
	s_nop 0
	global_load_lds_dwordx4 v252, s[24:25]
	s_add_i32 m0, s26, 0x8400
	s_nop 0
	global_load_lds_dwordx4 v253, s[24:25]
	s_add_u32 s24, s24, 0x50000
	s_addc_u32 s25, s25, 0

.Lgu_b292:
	v_add_f32_e32 v114, v114, v115
	v_fmac_f32_e32 v114, v202, v195
	s_cmpk_ge_u32 s26, 0x2010
	s_cbranch_scc1 .Lpp_b_pJ
	s_waitcnt vmcnt(0)
	s_barrier
	s_nop 0
	s_sub_u32 s36, s24, 0x50000
	s_subb_u32 s37, s25, 0
	s_add_i32 m0, s26, 0x4000
	s_nop 0
	global_load_lds_dwordx4 v250, s[36:37]
	s_add_i32 m0, s26, 0x4400
	s_nop 0
	global_load_lds_dwordx4 v251, s[36:37]
	s_add_i32 s38, s14, 1
	s_cmp_eq_u32 s38, s23
	s_cbranch_scc1 .Lpp_b_p_nok
	s_add_i32 m0, s26, 0x8000
	s_nop 0
	global_load_lds_dwordx4 v252, s[24:25]
	s_add_i32 m0, s26, 0x8400
	s_nop 0
	global_load_lds_dwordx4 v253, s[24:25]
	s_add_u32 s24, s24, 0x50000
	s_addc_u32 s25, s25, 0
.Lpp_b_p_nok:
.Lpp_b_pJ:
	ds_read_b64_tr_b16 v[116:117], v237 offset:0
	ds_read_b64_tr_b16 v[118:119], v237 offset:2048
	ds_read_b64_tr_b16 v[120:121], v237 offset:4096
	ds_read_b64_tr_b16 v[122:123], v237 offset:6144
	ds_read_b64_tr_b16 v[124:125], v237 offset:8192
	ds_read_b64_tr_b16 v[126:127], v237 offset:10240
	ds_read_b64_tr_b16 v[238:239], v237 offset:12288
	ds_read_b64_tr_b16 v[240:241], v237 offset:14336
	s_nop 0
	s_waitcnt lgkmcnt(6)
	v_mfma_f32_32x32x16_bf16 v[2:17], v[110:113], v[116:119], v[2:17]
	ds_read_b64_tr_b16 v[116:117], v237 offset:512
	ds_read_b64_tr_b16 v[118:119], v237 offset:2560
	s_waitcnt lgkmcnt(6)
	v_mfma_f32_32x32x16_bf16 v[2:17], v[106:109], v[120:123], v[2:17]
	ds_read_b64_tr_b16 v[120:121], v237 offset:4608
	ds_read_b64_tr_b16 v[122:123], v237 offset:6656
	s_waitcnt lgkmcnt(6)
	v_mfma_f32_32x32x16_bf16 v[2:17], v[102:105], v[124:127], v[2:17]
	ds_read_b64_tr_b16 v[124:125], v237 offset:8704
	ds_read_b64_tr_b16 v[126:127], v237 offset:10752
	s_waitcnt lgkmcnt(6)
	v_mfma_f32_32x32x16_bf16 v[2:17], v[98:101], v[238:241], v[2:17]
	ds_read_b64_tr_b16 v[238:239], v237 offset:12800
	ds_read_b64_tr_b16 v[240:241], v237 offset:14848
	s_waitcnt lgkmcnt(6)
	v_mfma_f32_32x32x16_bf16 v[18:33], v[110:113], v[116:119], v[18:33]
	ds_read_b64_tr_b16 v[116:117], v237 offset:1024
	ds_read_b64_tr_b16 v[118:119], v237 offset:3072
	s_waitcnt lgkmcnt(6)
	v_mfma_f32_32x32x16_bf16 v[18:33], v[106:109], v[120:123], v[18:33]
	ds_read_b64_tr_b16 v[120:121], v237 offset:5120
	ds_read_b64_tr_b16 v[122:123], v237 offset:7168
	s_waitcnt lgkmcnt(6)
	v_mfma_f32_32x32x16_bf16 v[18:33], v[102:105], v[124:127], v[18:33]
	ds_read_b64_tr_b16 v[124:125], v237 offset:9216
	ds_read_b64_tr_b16 v[126:127], v237 offset:11264
	s_waitcnt lgkmcnt(6)
	v_mfma_f32_32x32x16_bf16 v[18:33], v[98:101], v[238:241], v[18:33]
	ds_read_b64_tr_b16 v[238:239], v237 offset:13312
	ds_read_b64_tr_b16 v[240:241], v237 offset:15360
	s_waitcnt lgkmcnt(6)
	v_mfma_f32_32x32x16_bf16 v[34:49], v[110:113], v[116:119], v[34:49]
	ds_read_b64_tr_b16 v[116:117], v237 offset:1536
	ds_read_b64_tr_b16 v[118:119], v237 offset:3584
	s_waitcnt lgkmcnt(6)
	v_mfma_f32_32x32x16_bf16 v[34:49], v[106:109], v[120:123], v[34:49]
	ds_read_b64_tr_b16 v[120:121], v237 offset:5632
	ds_read_b64_tr_b16 v[122:123], v237 offset:7680
	s_waitcnt lgkmcnt(6)
	v_mfma_f32_32x32x16_bf16 v[34:49], v[102:105], v[124:127], v[34:49]
	ds_read_b64_tr_b16 v[124:125], v237 offset:9728
	ds_read_b64_tr_b16 v[126:127], v237 offset:11776
	s_waitcnt lgkmcnt(6)
	v_mfma_f32_32x32x16_bf16 v[34:49], v[98:101], v[238:241], v[34:49]
	ds_read_b64_tr_b16 v[238:239], v237 offset:13824
	ds_read_b64_tr_b16 v[240:241], v237 offset:15872
	s_waitcnt lgkmcnt(6)
	v_mfma_f32_32x32x16_bf16 v[50:65], v[110:113], v[116:119], v[50:65]
	s_add_i32 s14, s14, 1
	s_cmp_eq_u32 s23, s14
	s_waitcnt lgkmcnt(4)
	v_mfma_f32_32x32x16_bf16 v[50:65], v[106:109], v[120:123], v[50:65]
	s_waitcnt lgkmcnt(2)
	v_mfma_f32_32x32x16_bf16 v[50:65], v[102:105], v[124:127], v[50:65]
	s_waitcnt lgkmcnt(0)
	v_mfma_f32_32x32x16_bf16 v[50:65], v[98:101], v[238:241], v[50:65]
	s_cbranch_scc1 .LBB0_295
	v_mov_b32_e32 v202, v114
	s_branch .Lgu_a286

.LBB0_295:
	s_nop 0
	s_nop 0
	s_nop 0
	s_nop 0
	s_nop 0
	s_nop 0
	s_nop 0
	s_nop 0
	s_nop 0
	s_nop 0
	s_nop 0
	s_nop 0
	s_nop 0
	s_nop 0
	v_mov_b64_e32 v[82:83], v[66:67]
	v_mov_b64_e32 v[84:85], v[68:69]
	v_mov_b64_e32 v[86:87], v[70:71]
	v_mov_b64_e32 v[88:89], v[72:73]
	v_mov_b64_e32 v[90:91], v[74:75]
	v_mov_b64_e32 v[92:93], v[76:77]
	v_mov_b64_e32 v[94:95], v[78:79]
	v_mov_b64_e32 v[96:97], v[80:81]
	s_lshl_b32 s10, s14, 14
	s_addk_i32 s10, 0x4000
	s_and_b32 s12, s10, 0x4000
	v_add_u32_e32 v102, s12, v227
	v_add_u32_e32 v103, v102, v228
	ds_read_b128 v[98:101], v103 offset:32768
	s_waitcnt lgkmcnt(0)
	v_mfma_f32_32x32x16_bf16 v[66:81], v[98:101], v[134:137], v[82:97]
	ds_read_b128 v[98:101], v103 offset:40960
	v_add_u32_e32 v103, v102, v229
	s_waitcnt lgkmcnt(0)
	v_mfma_f32_32x32x16_bf16 v[82:97], v[98:101], v[134:137], v[82:97]
	ds_read_b128 v[98:101], v103 offset:32768
	s_waitcnt lgkmcnt(0)
	v_mfma_f32_32x32x16_bf16 v[66:81], v[98:101], v[142:145], v[66:81]
	ds_read_b128 v[98:101], v103 offset:40960
	v_add_u32_e32 v103, v102, v230
	s_waitcnt lgkmcnt(0)
	v_mfma_f32_32x32x16_bf16 v[82:97], v[98:101], v[142:145], v[82:97]
	ds_read_b128 v[98:101], v103 offset:32768
	s_waitcnt lgkmcnt(0)
	v_mfma_f32_32x32x16_bf16 v[66:81], v[98:101], v[146:149], v[66:81]
	ds_read_b128 v[98:101], v103 offset:40960
	v_add_u32_e32 v103, v102, v231
	s_waitcnt lgkmcnt(0)
	v_mfma_f32_32x32x16_bf16 v[82:97], v[98:101], v[146:149], v[82:97]
	ds_read_b128 v[98:101], v103 offset:32768
	s_waitcnt lgkmcnt(0)
	v_mfma_f32_32x32x16_bf16 v[66:81], v[98:101], v[150:153], v[66:81]
	ds_read_b128 v[98:101], v103 offset:40960
	v_add_u32_e32 v103, v102, v232
	s_waitcnt lgkmcnt(0)
	v_mfma_f32_32x32x16_bf16 v[82:97], v[98:101], v[150:153], v[82:97]
	ds_read_b128 v[98:101], v103 offset:32768
	s_waitcnt lgkmcnt(0)
	v_mfma_f32_32x32x16_bf16 v[66:81], v[98:101], v[154:157], v[66:81]
	ds_read_b128 v[98:101], v103 offset:40960
	v_add_u32_e32 v103, v102, v233
	s_waitcnt lgkmcnt(0)
	v_mfma_f32_32x32x16_bf16 v[82:97], v[98:101], v[154:157], v[82:97]
	ds_read_b128 v[98:101], v103 offset:32768
	s_waitcnt lgkmcnt(0)
	v_mfma_f32_32x32x16_bf16 v[66:81], v[98:101], v[158:161], v[66:81]
	ds_read_b128 v[98:101], v103 offset:40960
	v_add_u32_e32 v103, v102, v234
	v_add_u32_e32 v102, v102, v235
	s_waitcnt lgkmcnt(0)
	v_mfma_f32_32x32x16_bf16 v[82:97], v[98:101], v[158:161], v[82:97]
	ds_read_b128 v[98:101], v103 offset:32768
	s_waitcnt lgkmcnt(0)
	v_mfma_f32_32x32x16_bf16 v[66:81], v[98:101], v[138:141], v[66:81]
	ds_read_b128 v[98:101], v102 offset:32768
	s_waitcnt lgkmcnt(0)
	v_mfma_f32_32x32x16_bf16 v[66:81], v[98:101], v[130:133], v[66:81]
	ds_read_b128 v[98:101], v103 offset:40960
	ds_read_b128 v[102:105], v102 offset:40960
	s_waitcnt lgkmcnt(1)
	v_mfma_f32_32x32x16_bf16 v[82:97], v[98:101], v[138:141], v[82:97]
	s_nop 7
	v_max_f32_e32 v106, v67, v67
	v_max_f32_e32 v107, v66, v66
	v_max_f32_e32 v106, v107, v106
	v_max3_f32 v98, v106, v68, v69
	v_max3_f32 v98, v98, v70, v71
	v_max3_f32 v98, v98, v72, v73
	v_max3_f32 v98, v98, v74, v75
	s_waitcnt lgkmcnt(0)
	v_mfma_f32_32x32x16_bf16 v[82:97], v[102:105], v[130:133], v[82:97]
	v_max3_f32 v98, v98, v76, v77
	v_max3_f32 v98, v98, v78, v79
	v_max3_f32 v98, v98, v80, v81
	s_nop 8
	v_max3_f32 v98, v98, v82, v83
	v_max3_f32 v98, v98, v84, v85
	v_max3_f32 v98, v98, v86, v87
	v_max3_f32 v98, v98, v88, v89
	v_max3_f32 v98, v98, v90, v91
	v_max3_f32 v98, v98, v92, v93
	v_max3_f32 v98, v98, v94, v95
	v_max3_f32 v98, v98, v96, v97
	v_mov_b32_e32 v99, v98
	s_nop 1
	v_permlane32_swap_b32_e32 v98, v99
	v_max_f32_e32 v99, v99, v99
	v_max_f32_e32 v98, v98, v98
	v_max_f32_e32 v99, v98, v99
	v_cmp_ge_f32_e32 vcc, s64, v99
	s_cmp_eq_u64 vcc, exec
	v_mov_b32_e32 v98, 1.0
	s_cbranch_scc0 .LBB0_307

.LBB0_300:
	v_add_f32_e32 v82, v82, v83
	v_fmac_f32_e32 v82, v114, v98
	s_waitcnt vmcnt(0)
	s_barrier
	v_add_u32_e32 v83, s12, v237
	ds_read_b64_tr_b16 v[84:85], v83 offset:0
	ds_read_b64_tr_b16 v[86:87], v83 offset:0x800
	ds_read_b64_tr_b16 v[88:89], v83 offset:0x1000
	ds_read_b64_tr_b16 v[90:91], v83 offset:0x1800
	ds_read_b64_tr_b16 v[92:93], v83 offset:0x2000
	ds_read_b64_tr_b16 v[94:95], v83 offset:0x2800
	ds_read_b64_tr_b16 v[96:97], v83 offset:0x3000
	ds_read_b64_tr_b16 v[98:99], v83 offset:0x3800
	s_waitcnt lgkmcnt(0)
	s_nop 0
	v_mfma_f32_32x32x16_bf16 v[2:17], v[78:81], v[84:87], v[2:17]
	ds_read_b64_tr_b16 v[84:85], v83 offset:0x200
	ds_read_b64_tr_b16 v[86:87], v83 offset:0xa00
	v_mfma_f32_32x32x16_bf16 v[2:17], v[74:77], v[88:91], v[2:17]
	ds_read_b64_tr_b16 v[88:89], v83 offset:0x1200
	ds_read_b64_tr_b16 v[90:91], v83 offset:0x1a00
	v_mfma_f32_32x32x16_bf16 v[2:17], v[70:73], v[92:95], v[2:17]
	ds_read_b64_tr_b16 v[92:93], v83 offset:0x2200
	ds_read_b64_tr_b16 v[94:95], v83 offset:0x2a00
	v_mfma_f32_32x32x16_bf16 v[2:17], v[66:69], v[96:99], v[2:17]
	ds_read_b64_tr_b16 v[96:97], v83 offset:0x3200
	ds_read_b64_tr_b16 v[98:99], v83 offset:0x3a00
	s_waitcnt lgkmcnt(0)
	v_mfma_f32_32x32x16_bf16 v[18:33], v[78:81], v[84:87], v[18:33]
	ds_read_b64_tr_b16 v[84:85], v83 offset:0x400
	ds_read_b64_tr_b16 v[86:87], v83 offset:0xc00
	v_mfma_f32_32x32x16_bf16 v[18:33], v[74:77], v[88:91], v[18:33]
	ds_read_b64_tr_b16 v[88:89], v83 offset:0x1400
	ds_read_b64_tr_b16 v[90:91], v83 offset:0x1c00
	v_mfma_f32_32x32x16_bf16 v[18:33], v[70:73], v[92:95], v[18:33]
	ds_read_b64_tr_b16 v[92:93], v83 offset:0x2400
	ds_read_b64_tr_b16 v[94:95], v83 offset:0x2c00
	v_mfma_f32_32x32x16_bf16 v[18:33], v[66:69], v[96:99], v[18:33]
	ds_read_b64_tr_b16 v[96:97], v83 offset:0x3400
	ds_read_b64_tr_b16 v[98:99], v83 offset:0x3c00
	s_waitcnt lgkmcnt(0)
	v_mfma_f32_32x32x16_bf16 v[34:49], v[78:81], v[84:87], v[34:49]
	ds_read_b64_tr_b16 v[84:85], v83 offset:0x600
	ds_read_b64_tr_b16 v[86:87], v83 offset:0xe00
	v_mfma_f32_32x32x16_bf16 v[34:49], v[74:77], v[88:91], v[34:49]
	ds_read_b64_tr_b16 v[88:89], v83 offset:0x1600
	ds_read_b64_tr_b16 v[90:91], v83 offset:0x1e00
	v_mfma_f32_32x32x16_bf16 v[34:49], v[70:73], v[92:95], v[34:49]
	ds_read_b64_tr_b16 v[92:93], v83 offset:0x2600
	ds_read_b64_tr_b16 v[94:95], v83 offset:0x2e00
	v_mfma_f32_32x32x16_bf16 v[34:49], v[66:69], v[96:99], v[34:49]
	ds_read_b64_tr_b16 v[96:97], v83 offset:0x3600
	ds_read_b64_tr_b16 v[98:99], v83 offset:0x3e00
	s_waitcnt lgkmcnt(0)
	v_mfma_f32_32x32x16_bf16 v[50:65], v[78:81], v[84:87], v[50:65]
	s_and_b64 vcc, exec, s[6:7]
	s_barrier
	v_mfma_f32_32x32x16_bf16 v[50:65], v[74:77], v[88:91], v[50:65]
	v_mfma_f32_32x32x16_bf16 v[50:65], v[70:73], v[92:95], v[50:65]
	v_mfma_f32_32x32x16_bf16 v[50:65], v[66:69], v[96:99], v[50:65]
	s_cbranch_vccz .LBB0_304
	s_and_saveexec_b64 s[10:11], s[4:5]
	ds_write_b32 v236, v82
	s_or_b64 exec, exec, s[10:11]
	s_waitcnt lgkmcnt(0)
	v_add_u32_e32 v163, v220, v226
	ds_read_b128 v[130:133], v163
	ds_read_b128 v[134:137], v163 offset:32
	ds_read_b128 v[138:141], v163 offset:64
	ds_read_b128 v[142:145], v163 offset:96
	v_add3_u32 v162, v188, v190, v196
	s_mov_b32 s24, s8
	s_mov_b32 s25, s9
	global_load_ushort v66, v162, s[24:25] offset:3072
	global_load_ushort v67, v162, s[24:25] offset:3136
	global_load_ushort v68, v162, s[24:25] offset:3200
	global_load_ushort v69, v162, s[24:25] offset:3264
	s_add_u32 s24, s24, 0x1400
	s_addc_u32 s25, s25, 0
	global_load_ushort v70, v162, s[24:25] offset:3072
	global_load_ushort v71, v162, s[24:25] offset:3136
	global_load_ushort v72, v162, s[24:25] offset:3200
	global_load_ushort v73, v162, s[24:25] offset:3264
	s_add_u32 s24, s24, 0x1400
	s_addc_u32 s25, s25, 0
	global_load_ushort v74, v162, s[24:25] offset:3072
	global_load_ushort v75, v162, s[24:25] offset:3136
	global_load_ushort v76, v162, s[24:25] offset:3200
	global_load_ushort v77, v162, s[24:25] offset:3264
	s_add_u32 s24, s24, 0x1400
	s_addc_u32 s25, s25, 0
	global_load_ushort v78, v162, s[24:25] offset:3072
	global_load_ushort v79, v162, s[24:25] offset:3136
	global_load_ushort v80, v162, s[24:25] offset:3200
	global_load_ushort v81, v162, s[24:25] offset:3264
	s_add_u32 s24, s24, 0x6400
	s_addc_u32 s25, s25, 0
	global_load_ushort v82, v162, s[24:25] offset:3072
	global_load_ushort v83, v162, s[24:25] offset:3136
	global_load_ushort v84, v162, s[24:25] offset:3200
	global_load_ushort v85, v162, s[24:25] offset:3264
	s_add_u32 s24, s24, 0x1400
	s_addc_u32 s25, s25, 0
	global_load_ushort v86, v162, s[24:25] offset:3072
	global_load_ushort v87, v162, s[24:25] offset:3136
	global_load_ushort v88, v162, s[24:25] offset:3200
	global_load_ushort v89, v162, s[24:25] offset:3264
	s_add_u32 s24, s24, 0x1400
	s_addc_u32 s25, s25, 0
	global_load_ushort v90, v162, s[24:25] offset:3072
	global_load_ushort v91, v162, s[24:25] offset:3136
	global_load_ushort v92, v162, s[24:25] offset:3200
	global_load_ushort v93, v162, s[24:25] offset:3264
	s_add_u32 s24, s24, 0x1400
	s_addc_u32 s25, s25, 0
	global_load_ushort v94, v162, s[24:25] offset:3072
	global_load_ushort v95, v162, s[24:25] offset:3136
	global_load_ushort v96, v162, s[24:25] offset:3200
	global_load_ushort v97, v162, s[24:25] offset:3264
	s_add_u32 s24, s24, 0x6400
	s_addc_u32 s25, s25, 0
	global_load_ushort v98, v162, s[24:25] offset:3072
	global_load_ushort v99, v162, s[24:25] offset:3136
	global_load_ushort v100, v162, s[24:25] offset:3200
	global_load_ushort v101, v162, s[24:25] offset:3264
	s_add_u32 s24, s24, 0x1400
	s_addc_u32 s25, s25, 0
	global_load_ushort v102, v162, s[24:25] offset:3072
	global_load_ushort v103, v162, s[24:25] offset:3136
	global_load_ushort v104, v162, s[24:25] offset:3200
	global_load_ushort v105, v162, s[24:25] offset:3264
	s_add_u32 s24, s24, 0x1400
	s_addc_u32 s25, s25, 0
	global_load_ushort v106, v162, s[24:25] offset:3072
	global_load_ushort v107, v162, s[24:25] offset:3136
	global_load_ushort v108, v162, s[24:25] offset:3200
	global_load_ushort v109, v162, s[24:25] offset:3264
	s_add_u32 s24, s24, 0x1400
	s_addc_u32 s25, s25, 0
	global_load_ushort v110, v162, s[24:25] offset:3072
	global_load_ushort v111, v162, s[24:25] offset:3136
	global_load_ushort v112, v162, s[24:25] offset:3200
	global_load_ushort v113, v162, s[24:25] offset:3264
	s_add_u32 s24, s24, 0x6400
	s_addc_u32 s25, s25, 0
	global_load_ushort v114, v162, s[24:25] offset:3072
	global_load_ushort v115, v162, s[24:25] offset:3136
	global_load_ushort v116, v162, s[24:25] offset:3200
	global_load_ushort v117, v162, s[24:25] offset:3264
	s_add_u32 s24, s24, 0x1400
	s_addc_u32 s25, s25, 0
	global_load_ushort v118, v162, s[24:25] offset:3072
	global_load_ushort v119, v162, s[24:25] offset:3136
	global_load_ushort v120, v162, s[24:25] offset:3200
	global_load_ushort v121, v162, s[24:25] offset:3264
	s_add_u32 s24, s24, 0x1400
	s_addc_u32 s25, s25, 0
	global_load_ushort v122, v162, s[24:25] offset:3072
	global_load_ushort v123, v162, s[24:25] offset:3136
	global_load_ushort v124, v162, s[24:25] offset:3200
	global_load_ushort v125, v162, s[24:25] offset:3264
	s_add_u32 s24, s24, 0x1400
	s_addc_u32 s25, s25, 0
	global_load_ushort v126, v162, s[24:25] offset:3072
	global_load_ushort v127, v162, s[24:25] offset:3136
	global_load_ushort v128, v162, s[24:25] offset:3200
	global_load_ushort v129, v162, s[24:25] offset:3264
	s_waitcnt lgkmcnt(0)
	v_rcp_f32_e32 v146, v130
	v_rcp_f32_e32 v147, v131
	v_rcp_f32_e32 v148, v132
	v_rcp_f32_e32 v149, v133
	v_rcp_f32_e32 v150, v134
	v_rcp_f32_e32 v151, v135
	v_rcp_f32_e32 v152, v136
	v_rcp_f32_e32 v153, v137
	v_rcp_f32_e32 v154, v138
	v_rcp_f32_e32 v155, v139
	v_rcp_f32_e32 v156, v140
	v_rcp_f32_e32 v157, v141
	v_rcp_f32_e32 v158, v142
	v_rcp_f32_e32 v159, v143
	v_rcp_f32_e32 v160, v144
	v_rcp_f32_e32 v161, v145
	s_waitcnt vmcnt(62)
	v_lshlrev_b32_e32 v66, 16, v66
	v_lshlrev_b32_e32 v67, 16, v67
	v_mul_f32_e32 v164, 0xbfb8aa3b, v66
	v_mul_f32_e32 v165, 0xbfb8aa3b, v67
	v_exp_f32_e32 v164, v164
	v_exp_f32_e32 v165, v165
	v_mul_f32_e32 v166, v2, v146
	v_mul_f32_e32 v167, v18, v146
	v_add_f32_e32 v164, 1.0, v164
	v_add_f32_e32 v165, 1.0, v165
	v_rcp_f32_e32 v164, v164
	v_rcp_f32_e32 v165, v165
	s_nop 0
	v_mul_f32_e32 v66, v164, v66
	v_mul_f32_e32 v67, v165, v67
	v_mul_f32_e32 v66, v166, v66
	v_mul_f32_e32 v67, v167, v67
	v_cvt_pk_bf16_f32 v66, v66, v66
	v_cvt_pk_bf16_f32 v67, v67, v67
	s_waitcnt vmcnt(60)
	v_lshlrev_b32_e32 v68, 16, v68
	v_lshlrev_b32_e32 v69, 16, v69
	v_mul_f32_e32 v164, 0xbfb8aa3b, v68
	v_mul_f32_e32 v165, 0xbfb8aa3b, v69
	v_exp_f32_e32 v164, v164
	v_exp_f32_e32 v165, v165
	v_mul_f32_e32 v166, v34, v146
	v_mul_f32_e32 v167, v50, v146
	v_add_f32_e32 v164, 1.0, v164
	v_add_f32_e32 v165, 1.0, v165
	v_rcp_f32_e32 v164, v164
	v_rcp_f32_e32 v165, v165
	s_nop 0
	v_mul_f32_e32 v68, v164, v68
	v_mul_f32_e32 v69, v165, v69
	v_mul_f32_e32 v68, v166, v68
	v_mul_f32_e32 v69, v167, v69
	v_cvt_pk_bf16_f32 v68, v68, v68
	v_cvt_pk_bf16_f32 v69, v69, v69
	s_waitcnt vmcnt(58)
	v_lshlrev_b32_e32 v70, 16, v70
	v_lshlrev_b32_e32 v71, 16, v71
	v_mul_f32_e32 v164, 0xbfb8aa3b, v70
	v_mul_f32_e32 v165, 0xbfb8aa3b, v71
	v_exp_f32_e32 v164, v164
	v_exp_f32_e32 v165, v165
	v_mul_f32_e32 v166, v3, v147
	v_mul_f32_e32 v167, v19, v147
	v_add_f32_e32 v164, 1.0, v164
	v_add_f32_e32 v165, 1.0, v165
	v_rcp_f32_e32 v164, v164
	v_rcp_f32_e32 v165, v165
	s_nop 0
	v_mul_f32_e32 v70, v164, v70
	v_mul_f32_e32 v71, v165, v71
	v_mul_f32_e32 v70, v166, v70
	v_mul_f32_e32 v71, v167, v71
	v_cvt_pk_bf16_f32 v70, v70, v70
	v_cvt_pk_bf16_f32 v71, v71, v71
	s_waitcnt vmcnt(56)
	v_lshlrev_b32_e32 v72, 16, v72
	v_lshlrev_b32_e32 v73, 16, v73
	v_mul_f32_e32 v164, 0xbfb8aa3b, v72
	v_mul_f32_e32 v165, 0xbfb8aa3b, v73
	v_exp_f32_e32 v164, v164
	v_exp_f32_e32 v165, v165
	v_mul_f32_e32 v166, v35, v147
	v_mul_f32_e32 v167, v51, v147
	v_add_f32_e32 v164, 1.0, v164
	v_add_f32_e32 v165, 1.0, v165
	v_rcp_f32_e32 v164, v164
	v_rcp_f32_e32 v165, v165
	s_nop 0
	v_mul_f32_e32 v72, v164, v72
	v_mul_f32_e32 v73, v165, v73
	v_mul_f32_e32 v72, v166, v72
	v_mul_f32_e32 v73, v167, v73
	v_cvt_pk_bf16_f32 v72, v72, v72
	v_cvt_pk_bf16_f32 v73, v73, v73
	s_waitcnt vmcnt(54)
	v_lshlrev_b32_e32 v74, 16, v74
	v_lshlrev_b32_e32 v75, 16, v75
	v_mul_f32_e32 v164, 0xbfb8aa3b, v74
	v_mul_f32_e32 v165, 0xbfb8aa3b, v75
	v_exp_f32_e32 v164, v164
	v_exp_f32_e32 v165, v165
	v_mul_f32_e32 v166, v4, v148
	v_mul_f32_e32 v167, v20, v148
	v_add_f32_e32 v164, 1.0, v164
	v_add_f32_e32 v165, 1.0, v165
	v_rcp_f32_e32 v164, v164
	v_rcp_f32_e32 v165, v165
	s_nop 0
	v_mul_f32_e32 v74, v164, v74
	v_mul_f32_e32 v75, v165, v75
	v_mul_f32_e32 v74, v166, v74
	v_mul_f32_e32 v75, v167, v75
	v_cvt_pk_bf16_f32 v74, v74, v74
	v_cvt_pk_bf16_f32 v75, v75, v75
	s_waitcnt vmcnt(52)
	v_lshlrev_b32_e32 v76, 16, v76
	v_lshlrev_b32_e32 v77, 16, v77
	v_mul_f32_e32 v164, 0xbfb8aa3b, v76
	v_mul_f32_e32 v165, 0xbfb8aa3b, v77
	v_exp_f32_e32 v164, v164
	v_exp_f32_e32 v165, v165
	v_mul_f32_e32 v166, v36, v148
	v_mul_f32_e32 v167, v52, v148
	v_add_f32_e32 v164, 1.0, v164
	v_add_f32_e32 v165, 1.0, v165
	v_rcp_f32_e32 v164, v164
	v_rcp_f32_e32 v165, v165
	s_nop 0
	v_mul_f32_e32 v76, v164, v76
	v_mul_f32_e32 v77, v165, v77
	v_mul_f32_e32 v76, v166, v76
	v_mul_f32_e32 v77, v167, v77
	v_cvt_pk_bf16_f32 v76, v76, v76
	v_cvt_pk_bf16_f32 v77, v77, v77
	s_waitcnt vmcnt(50)
	v_lshlrev_b32_e32 v78, 16, v78
	v_lshlrev_b32_e32 v79, 16, v79
	v_mul_f32_e32 v164, 0xbfb8aa3b, v78
	v_mul_f32_e32 v165, 0xbfb8aa3b, v79
	v_exp_f32_e32 v164, v164
	v_exp_f32_e32 v165, v165
	v_mul_f32_e32 v166, v5, v149
	v_mul_f32_e32 v167, v21, v149
	v_add_f32_e32 v164, 1.0, v164
	v_add_f32_e32 v165, 1.0, v165
	v_rcp_f32_e32 v164, v164
	v_rcp_f32_e32 v165, v165
	s_nop 0
	v_mul_f32_e32 v78, v164, v78
	v_mul_f32_e32 v79, v165, v79
	v_mul_f32_e32 v78, v166, v78
	v_mul_f32_e32 v79, v167, v79
	v_cvt_pk_bf16_f32 v78, v78, v78
	v_cvt_pk_bf16_f32 v79, v79, v79
	s_waitcnt vmcnt(48)
	v_lshlrev_b32_e32 v80, 16, v80
	v_lshlrev_b32_e32 v81, 16, v81
	v_mul_f32_e32 v164, 0xbfb8aa3b, v80
	v_mul_f32_e32 v165, 0xbfb8aa3b, v81
	v_exp_f32_e32 v164, v164
	v_exp_f32_e32 v165, v165
	v_mul_f32_e32 v166, v37, v149
	v_mul_f32_e32 v167, v53, v149
	v_add_f32_e32 v164, 1.0, v164
	v_add_f32_e32 v165, 1.0, v165
	v_rcp_f32_e32 v164, v164
	v_rcp_f32_e32 v165, v165
	s_nop 0
	v_mul_f32_e32 v80, v164, v80
	v_mul_f32_e32 v81, v165, v81
	v_mul_f32_e32 v80, v166, v80
	v_mul_f32_e32 v81, v167, v81
	v_cvt_pk_bf16_f32 v80, v80, v80
	v_cvt_pk_bf16_f32 v81, v81, v81
	s_waitcnt vmcnt(46)
	v_lshlrev_b32_e32 v82, 16, v82
	v_lshlrev_b32_e32 v83, 16, v83
	v_mul_f32_e32 v164, 0xbfb8aa3b, v82
	v_mul_f32_e32 v165, 0xbfb8aa3b, v83
	v_exp_f32_e32 v164, v164
	v_exp_f32_e32 v165, v165
	v_mul_f32_e32 v166, v6, v150
	v_mul_f32_e32 v167, v22, v150
	v_add_f32_e32 v164, 1.0, v164
	v_add_f32_e32 v165, 1.0, v165
	v_rcp_f32_e32 v164, v164
	v_rcp_f32_e32 v165, v165
	s_nop 0
	v_mul_f32_e32 v82, v164, v82
	v_mul_f32_e32 v83, v165, v83
	v_mul_f32_e32 v82, v166, v82
	v_mul_f32_e32 v83, v167, v83
	v_cvt_pk_bf16_f32 v82, v82, v82
	v_cvt_pk_bf16_f32 v83, v83, v83
	s_waitcnt vmcnt(44)
	v_lshlrev_b32_e32 v84, 16, v84
	v_lshlrev_b32_e32 v85, 16, v85
	v_mul_f32_e32 v164, 0xbfb8aa3b, v84
	v_mul_f32_e32 v165, 0xbfb8aa3b, v85
	v_exp_f32_e32 v164, v164
	v_exp_f32_e32 v165, v165
	v_mul_f32_e32 v166, v38, v150
	v_mul_f32_e32 v167, v54, v150
	v_add_f32_e32 v164, 1.0, v164
	v_add_f32_e32 v165, 1.0, v165
	v_rcp_f32_e32 v164, v164
	v_rcp_f32_e32 v165, v165
	s_nop 0
	v_mul_f32_e32 v84, v164, v84
	v_mul_f32_e32 v85, v165, v85
	v_mul_f32_e32 v84, v166, v84
	v_mul_f32_e32 v85, v167, v85
	v_cvt_pk_bf16_f32 v84, v84, v84
	v_cvt_pk_bf16_f32 v85, v85, v85
	s_waitcnt vmcnt(42)
	v_lshlrev_b32_e32 v86, 16, v86
	v_lshlrev_b32_e32 v87, 16, v87
	v_mul_f32_e32 v164, 0xbfb8aa3b, v86
	v_mul_f32_e32 v165, 0xbfb8aa3b, v87
	v_exp_f32_e32 v164, v164
	v_exp_f32_e32 v165, v165
	v_mul_f32_e32 v166, v7, v151
	v_mul_f32_e32 v167, v23, v151
	v_add_f32_e32 v164, 1.0, v164
	v_add_f32_e32 v165, 1.0, v165
	v_rcp_f32_e32 v164, v164
	v_rcp_f32_e32 v165, v165
	s_nop 0
	v_mul_f32_e32 v86, v164, v86
	v_mul_f32_e32 v87, v165, v87
	v_mul_f32_e32 v86, v166, v86
	v_mul_f32_e32 v87, v167, v87
	v_cvt_pk_bf16_f32 v86, v86, v86
	v_cvt_pk_bf16_f32 v87, v87, v87
	s_waitcnt vmcnt(40)
	v_lshlrev_b32_e32 v88, 16, v88
	v_lshlrev_b32_e32 v89, 16, v89
	v_mul_f32_e32 v164, 0xbfb8aa3b, v88
	v_mul_f32_e32 v165, 0xbfb8aa3b, v89
	v_exp_f32_e32 v164, v164
	v_exp_f32_e32 v165, v165
	v_mul_f32_e32 v166, v39, v151
	v_mul_f32_e32 v167, v55, v151
	v_add_f32_e32 v164, 1.0, v164
	v_add_f32_e32 v165, 1.0, v165
	v_rcp_f32_e32 v164, v164
	v_rcp_f32_e32 v165, v165
	s_nop 0
	v_mul_f32_e32 v88, v164, v88
	v_mul_f32_e32 v89, v165, v89
	v_mul_f32_e32 v88, v166, v88
	v_mul_f32_e32 v89, v167, v89
	v_cvt_pk_bf16_f32 v88, v88, v88
	v_cvt_pk_bf16_f32 v89, v89, v89
	s_waitcnt vmcnt(38)
	v_lshlrev_b32_e32 v90, 16, v90
	v_lshlrev_b32_e32 v91, 16, v91
	v_mul_f32_e32 v164, 0xbfb8aa3b, v90
	v_mul_f32_e32 v165, 0xbfb8aa3b, v91
	v_exp_f32_e32 v164, v164
	v_exp_f32_e32 v165, v165
	v_mul_f32_e32 v166, v8, v152
	v_mul_f32_e32 v167, v24, v152
	v_add_f32_e32 v164, 1.0, v164
	v_add_f32_e32 v165, 1.0, v165
	v_rcp_f32_e32 v164, v164
	v_rcp_f32_e32 v165, v165
	s_nop 0
	v_mul_f32_e32 v90, v164, v90
	v_mul_f32_e32 v91, v165, v91
	v_mul_f32_e32 v90, v166, v90
	v_mul_f32_e32 v91, v167, v91
	v_cvt_pk_bf16_f32 v90, v90, v90
	v_cvt_pk_bf16_f32 v91, v91, v91
	s_waitcnt vmcnt(36)
	v_lshlrev_b32_e32 v92, 16, v92
	v_lshlrev_b32_e32 v93, 16, v93
	v_mul_f32_e32 v164, 0xbfb8aa3b, v92
	v_mul_f32_e32 v165, 0xbfb8aa3b, v93
	v_exp_f32_e32 v164, v164
	v_exp_f32_e32 v165, v165
	v_mul_f32_e32 v166, v40, v152
	v_mul_f32_e32 v167, v56, v152
	v_add_f32_e32 v164, 1.0, v164
	v_add_f32_e32 v165, 1.0, v165
	v_rcp_f32_e32 v164, v164
	v_rcp_f32_e32 v165, v165
	s_nop 0
	v_mul_f32_e32 v92, v164, v92
	v_mul_f32_e32 v93, v165, v93
	v_mul_f32_e32 v92, v166, v92
	v_mul_f32_e32 v93, v167, v93
	v_cvt_pk_bf16_f32 v92, v92, v92
	v_cvt_pk_bf16_f32 v93, v93, v93
	s_waitcnt vmcnt(34)
	v_lshlrev_b32_e32 v94, 16, v94
	v_lshlrev_b32_e32 v95, 16, v95
	v_mul_f32_e32 v164, 0xbfb8aa3b, v94
	v_mul_f32_e32 v165, 0xbfb8aa3b, v95
	v_exp_f32_e32 v164, v164
	v_exp_f32_e32 v165, v165
	v_mul_f32_e32 v166, v9, v153
	v_mul_f32_e32 v167, v25, v153
	v_add_f32_e32 v164, 1.0, v164
	v_add_f32_e32 v165, 1.0, v165
	v_rcp_f32_e32 v164, v164
	v_rcp_f32_e32 v165, v165
	s_nop 0
	v_mul_f32_e32 v94, v164, v94
	v_mul_f32_e32 v95, v165, v95
	v_mul_f32_e32 v94, v166, v94
	v_mul_f32_e32 v95, v167, v95
	v_cvt_pk_bf16_f32 v94, v94, v94
	v_cvt_pk_bf16_f32 v95, v95, v95
	s_waitcnt vmcnt(32)
	v_lshlrev_b32_e32 v96, 16, v96
	v_lshlrev_b32_e32 v97, 16, v97
	v_mul_f32_e32 v164, 0xbfb8aa3b, v96
	v_mul_f32_e32 v165, 0xbfb8aa3b, v97
	v_exp_f32_e32 v164, v164
	v_exp_f32_e32 v165, v165
	v_mul_f32_e32 v166, v41, v153
	v_mul_f32_e32 v167, v57, v153
	v_add_f32_e32 v164, 1.0, v164
	v_add_f32_e32 v165, 1.0, v165
	v_rcp_f32_e32 v164, v164
	v_rcp_f32_e32 v165, v165
	s_nop 0
	v_mul_f32_e32 v96, v164, v96
	v_mul_f32_e32 v97, v165, v97
	v_mul_f32_e32 v96, v166, v96
	v_mul_f32_e32 v97, v167, v97
	v_cvt_pk_bf16_f32 v96, v96, v96
	v_cvt_pk_bf16_f32 v97, v97, v97
	s_waitcnt vmcnt(30)
	v_lshlrev_b32_e32 v98, 16, v98
	v_lshlrev_b32_e32 v99, 16, v99
	v_mul_f32_e32 v164, 0xbfb8aa3b, v98
	v_mul_f32_e32 v165, 0xbfb8aa3b, v99
	v_exp_f32_e32 v164, v164
	v_exp_f32_e32 v165, v165
	v_mul_f32_e32 v166, v10, v154
	v_mul_f32_e32 v167, v26, v154
	v_add_f32_e32 v164, 1.0, v164
	v_add_f32_e32 v165, 1.0, v165
	v_rcp_f32_e32 v164, v164
	v_rcp_f32_e32 v165, v165
	s_nop 0
	v_mul_f32_e32 v98, v164, v98
	v_mul_f32_e32 v99, v165, v99
	v_mul_f32_e32 v98, v166, v98
	v_mul_f32_e32 v99, v167, v99
	v_cvt_pk_bf16_f32 v98, v98, v98
	v_cvt_pk_bf16_f32 v99, v99, v99
	s_waitcnt vmcnt(28)
	v_lshlrev_b32_e32 v100, 16, v100
	v_lshlrev_b32_e32 v101, 16, v101
	v_mul_f32_e32 v164, 0xbfb8aa3b, v100
	v_mul_f32_e32 v165, 0xbfb8aa3b, v101
	v_exp_f32_e32 v164, v164
	v_exp_f32_e32 v165, v165
	v_mul_f32_e32 v166, v42, v154
	v_mul_f32_e32 v167, v58, v154
	v_add_f32_e32 v164, 1.0, v164
	v_add_f32_e32 v165, 1.0, v165
	v_rcp_f32_e32 v164, v164
	v_rcp_f32_e32 v165, v165
	s_nop 0
	v_mul_f32_e32 v100, v164, v100
	v_mul_f32_e32 v101, v165, v101
	v_mul_f32_e32 v100, v166, v100
	v_mul_f32_e32 v101, v167, v101
	v_cvt_pk_bf16_f32 v100, v100, v100
	v_cvt_pk_bf16_f32 v101, v101, v101
	s_waitcnt vmcnt(26)
	v_lshlrev_b32_e32 v102, 16, v102
	v_lshlrev_b32_e32 v103, 16, v103
	v_mul_f32_e32 v164, 0xbfb8aa3b, v102
	v_mul_f32_e32 v165, 0xbfb8aa3b, v103
	v_exp_f32_e32 v164, v164
	v_exp_f32_e32 v165, v165
	v_mul_f32_e32 v166, v11, v155
	v_mul_f32_e32 v167, v27, v155
	v_add_f32_e32 v164, 1.0, v164
	v_add_f32_e32 v165, 1.0, v165
	v_rcp_f32_e32 v164, v164
	v_rcp_f32_e32 v165, v165
	s_nop 0
	v_mul_f32_e32 v102, v164, v102
	v_mul_f32_e32 v103, v165, v103
	v_mul_f32_e32 v102, v166, v102
	v_mul_f32_e32 v103, v167, v103
	v_cvt_pk_bf16_f32 v102, v102, v102
	v_cvt_pk_bf16_f32 v103, v103, v103
	s_waitcnt vmcnt(24)
	v_lshlrev_b32_e32 v104, 16, v104
	v_lshlrev_b32_e32 v105, 16, v105
	v_mul_f32_e32 v164, 0xbfb8aa3b, v104
	v_mul_f32_e32 v165, 0xbfb8aa3b, v105
	v_exp_f32_e32 v164, v164
	v_exp_f32_e32 v165, v165
	v_mul_f32_e32 v166, v43, v155
	v_mul_f32_e32 v167, v59, v155
	v_add_f32_e32 v164, 1.0, v164
	v_add_f32_e32 v165, 1.0, v165
	v_rcp_f32_e32 v164, v164
	v_rcp_f32_e32 v165, v165
	s_nop 0
	v_mul_f32_e32 v104, v164, v104
	v_mul_f32_e32 v105, v165, v105
	v_mul_f32_e32 v104, v166, v104
	v_mul_f32_e32 v105, v167, v105
	v_cvt_pk_bf16_f32 v104, v104, v104
	v_cvt_pk_bf16_f32 v105, v105, v105
	s_waitcnt vmcnt(22)
	v_lshlrev_b32_e32 v106, 16, v106
	v_lshlrev_b32_e32 v107, 16, v107
	v_mul_f32_e32 v164, 0xbfb8aa3b, v106
	v_mul_f32_e32 v165, 0xbfb8aa3b, v107
	v_exp_f32_e32 v164, v164
	v_exp_f32_e32 v165, v165
	v_mul_f32_e32 v166, v12, v156
	v_mul_f32_e32 v167, v28, v156
	v_add_f32_e32 v164, 1.0, v164
	v_add_f32_e32 v165, 1.0, v165
	v_rcp_f32_e32 v164, v164
	v_rcp_f32_e32 v165, v165
	s_nop 0
	v_mul_f32_e32 v106, v164, v106
	v_mul_f32_e32 v107, v165, v107
	v_mul_f32_e32 v106, v166, v106
	v_mul_f32_e32 v107, v167, v107
	v_cvt_pk_bf16_f32 v106, v106, v106
	v_cvt_pk_bf16_f32 v107, v107, v107
	s_waitcnt vmcnt(20)
	v_lshlrev_b32_e32 v108, 16, v108
	v_lshlrev_b32_e32 v109, 16, v109
	v_mul_f32_e32 v164, 0xbfb8aa3b, v108
	v_mul_f32_e32 v165, 0xbfb8aa3b, v109
	v_exp_f32_e32 v164, v164
	v_exp_f32_e32 v165, v165
	v_mul_f32_e32 v166, v44, v156
	v_mul_f32_e32 v167, v60, v156
	v_add_f32_e32 v164, 1.0, v164
	v_add_f32_e32 v165, 1.0, v165
	v_rcp_f32_e32 v164, v164
	v_rcp_f32_e32 v165, v165
	s_nop 0
	v_mul_f32_e32 v108, v164, v108
	v_mul_f32_e32 v109, v165, v109
	v_mul_f32_e32 v108, v166, v108
	v_mul_f32_e32 v109, v167, v109
	v_cvt_pk_bf16_f32 v108, v108, v108
	v_cvt_pk_bf16_f32 v109, v109, v109
	s_waitcnt vmcnt(18)
	v_lshlrev_b32_e32 v110, 16, v110
	v_lshlrev_b32_e32 v111, 16, v111
	v_mul_f32_e32 v164, 0xbfb8aa3b, v110
	v_mul_f32_e32 v165, 0xbfb8aa3b, v111
	v_exp_f32_e32 v164, v164
	v_exp_f32_e32 v165, v165
	v_mul_f32_e32 v166, v13, v157
	v_mul_f32_e32 v167, v29, v157
	v_add_f32_e32 v164, 1.0, v164
	v_add_f32_e32 v165, 1.0, v165
	v_rcp_f32_e32 v164, v164
	v_rcp_f32_e32 v165, v165
	s_nop 0
	v_mul_f32_e32 v110, v164, v110
	v_mul_f32_e32 v111, v165, v111
	v_mul_f32_e32 v110, v166, v110
	v_mul_f32_e32 v111, v167, v111
	v_cvt_pk_bf16_f32 v110, v110, v110
	v_cvt_pk_bf16_f32 v111, v111, v111
	s_waitcnt vmcnt(16)
	v_lshlrev_b32_e32 v112, 16, v112
	v_lshlrev_b32_e32 v113, 16, v113
	v_mul_f32_e32 v164, 0xbfb8aa3b, v112
	v_mul_f32_e32 v165, 0xbfb8aa3b, v113
	v_exp_f32_e32 v164, v164
	v_exp_f32_e32 v165, v165
	v_mul_f32_e32 v166, v45, v157
	v_mul_f32_e32 v167, v61, v157
	v_add_f32_e32 v164, 1.0, v164
	v_add_f32_e32 v165, 1.0, v165
	v_rcp_f32_e32 v164, v164
	v_rcp_f32_e32 v165, v165
	s_nop 0
	v_mul_f32_e32 v112, v164, v112
	v_mul_f32_e32 v113, v165, v113
	v_mul_f32_e32 v112, v166, v112
	v_mul_f32_e32 v113, v167, v113
	v_cvt_pk_bf16_f32 v112, v112, v112
	v_cvt_pk_bf16_f32 v113, v113, v113
	s_waitcnt vmcnt(14)
	v_lshlrev_b32_e32 v114, 16, v114
	v_lshlrev_b32_e32 v115, 16, v115
	v_mul_f32_e32 v164, 0xbfb8aa3b, v114
	v_mul_f32_e32 v165, 0xbfb8aa3b, v115
	v_exp_f32_e32 v164, v164
	v_exp_f32_e32 v165, v165
	v_mul_f32_e32 v166, v14, v158
	v_mul_f32_e32 v167, v30, v158
	v_add_f32_e32 v164, 1.0, v164
	v_add_f32_e32 v165, 1.0, v165
	v_rcp_f32_e32 v164, v164
	v_rcp_f32_e32 v165, v165
	s_nop 0
	v_mul_f32_e32 v114, v164, v114
	v_mul_f32_e32 v115, v165, v115
	v_mul_f32_e32 v114, v166, v114
	v_mul_f32_e32 v115, v167, v115
	v_cvt_pk_bf16_f32 v114, v114, v114
	v_cvt_pk_bf16_f32 v115, v115, v115
	s_waitcnt vmcnt(12)
	v_lshlrev_b32_e32 v116, 16, v116
	v_lshlrev_b32_e32 v117, 16, v117
	v_mul_f32_e32 v164, 0xbfb8aa3b, v116
	v_mul_f32_e32 v165, 0xbfb8aa3b, v117
	v_exp_f32_e32 v164, v164
	v_exp_f32_e32 v165, v165
	v_mul_f32_e32 v166, v46, v158
	v_mul_f32_e32 v167, v62, v158
	v_add_f32_e32 v164, 1.0, v164
	v_add_f32_e32 v165, 1.0, v165
	v_rcp_f32_e32 v164, v164
	v_rcp_f32_e32 v165, v165
	s_nop 0
	v_mul_f32_e32 v116, v164, v116
	v_mul_f32_e32 v117, v165, v117
	v_mul_f32_e32 v116, v166, v116
	v_mul_f32_e32 v117, v167, v117
	v_cvt_pk_bf16_f32 v116, v116, v116
	v_cvt_pk_bf16_f32 v117, v117, v117
	s_waitcnt vmcnt(10)
	v_lshlrev_b32_e32 v118, 16, v118
	v_lshlrev_b32_e32 v119, 16, v119
	v_mul_f32_e32 v164, 0xbfb8aa3b, v118
	v_mul_f32_e32 v165, 0xbfb8aa3b, v119
	v_exp_f32_e32 v164, v164
	v_exp_f32_e32 v165, v165
	v_mul_f32_e32 v166, v15, v159
	v_mul_f32_e32 v167, v31, v159
	v_add_f32_e32 v164, 1.0, v164
	v_add_f32_e32 v165, 1.0, v165
	v_rcp_f32_e32 v164, v164
	v_rcp_f32_e32 v165, v165
	s_nop 0
	v_mul_f32_e32 v118, v164, v118
	v_mul_f32_e32 v119, v165, v119
	v_mul_f32_e32 v118, v166, v118
	v_mul_f32_e32 v119, v167, v119
	v_cvt_pk_bf16_f32 v118, v118, v118
	v_cvt_pk_bf16_f32 v119, v119, v119
	s_waitcnt vmcnt(8)
	v_lshlrev_b32_e32 v120, 16, v120
	v_lshlrev_b32_e32 v121, 16, v121
	v_mul_f32_e32 v164, 0xbfb8aa3b, v120
	v_mul_f32_e32 v165, 0xbfb8aa3b, v121
	v_exp_f32_e32 v164, v164
	v_exp_f32_e32 v165, v165
	v_mul_f32_e32 v166, v47, v159
	v_mul_f32_e32 v167, v63, v159
	v_add_f32_e32 v164, 1.0, v164
	v_add_f32_e32 v165, 1.0, v165
	v_rcp_f32_e32 v164, v164
	v_rcp_f32_e32 v165, v165
	s_nop 0
	v_mul_f32_e32 v120, v164, v120
	v_mul_f32_e32 v121, v165, v121
	v_mul_f32_e32 v120, v166, v120
	v_mul_f32_e32 v121, v167, v121
	v_cvt_pk_bf16_f32 v120, v120, v120
	v_cvt_pk_bf16_f32 v121, v121, v121
	s_waitcnt vmcnt(6)
	v_lshlrev_b32_e32 v122, 16, v122
	v_lshlrev_b32_e32 v123, 16, v123
	v_mul_f32_e32 v164, 0xbfb8aa3b, v122
	v_mul_f32_e32 v165, 0xbfb8aa3b, v123
	v_exp_f32_e32 v164, v164
	v_exp_f32_e32 v165, v165
	v_mul_f32_e32 v166, v16, v160
	v_mul_f32_e32 v167, v32, v160
	v_add_f32_e32 v164, 1.0, v164
	v_add_f32_e32 v165, 1.0, v165
	v_rcp_f32_e32 v164, v164
	v_rcp_f32_e32 v165, v165
	s_nop 0
	v_mul_f32_e32 v122, v164, v122
	v_mul_f32_e32 v123, v165, v123
	v_mul_f32_e32 v122, v166, v122
	v_mul_f32_e32 v123, v167, v123
	v_cvt_pk_bf16_f32 v122, v122, v122
	v_cvt_pk_bf16_f32 v123, v123, v123
	s_waitcnt vmcnt(4)
	v_lshlrev_b32_e32 v124, 16, v124
	v_lshlrev_b32_e32 v125, 16, v125
	v_mul_f32_e32 v164, 0xbfb8aa3b, v124
	v_mul_f32_e32 v165, 0xbfb8aa3b, v125
	v_exp_f32_e32 v164, v164
	v_exp_f32_e32 v165, v165
	v_mul_f32_e32 v166, v48, v160
	v_mul_f32_e32 v167, v64, v160
	v_add_f32_e32 v164, 1.0, v164
	v_add_f32_e32 v165, 1.0, v165
	v_rcp_f32_e32 v164, v164
	v_rcp_f32_e32 v165, v165
	s_nop 0
	v_mul_f32_e32 v124, v164, v124
	v_mul_f32_e32 v125, v165, v125
	v_mul_f32_e32 v124, v166, v124
	v_mul_f32_e32 v125, v167, v125
	v_cvt_pk_bf16_f32 v124, v124, v124
	v_cvt_pk_bf16_f32 v125, v125, v125
	s_waitcnt vmcnt(2)
	v_lshlrev_b32_e32 v126, 16, v126
	v_lshlrev_b32_e32 v127, 16, v127
	v_mul_f32_e32 v164, 0xbfb8aa3b, v126
	v_mul_f32_e32 v165, 0xbfb8aa3b, v127
	v_exp_f32_e32 v164, v164
	v_exp_f32_e32 v165, v165
	v_mul_f32_e32 v166, v17, v161
	v_mul_f32_e32 v167, v33, v161
	v_add_f32_e32 v164, 1.0, v164
	v_add_f32_e32 v165, 1.0, v165
	v_rcp_f32_e32 v164, v164
	v_rcp_f32_e32 v165, v165
	s_nop 0
	v_mul_f32_e32 v126, v164, v126
	v_mul_f32_e32 v127, v165, v127
	v_mul_f32_e32 v126, v166, v126
	v_mul_f32_e32 v127, v167, v127
	v_cvt_pk_bf16_f32 v126, v126, v126
	v_cvt_pk_bf16_f32 v127, v127, v127
	s_waitcnt vmcnt(0)
	v_lshlrev_b32_e32 v128, 16, v128
	v_lshlrev_b32_e32 v129, 16, v129
	v_mul_f32_e32 v164, 0xbfb8aa3b, v128
	v_mul_f32_e32 v165, 0xbfb8aa3b, v129
	v_exp_f32_e32 v164, v164
	v_exp_f32_e32 v165, v165
	v_mul_f32_e32 v166, v49, v161
	v_mul_f32_e32 v167, v65, v161
	v_add_f32_e32 v164, 1.0, v164
	v_add_f32_e32 v165, 1.0, v165
	v_rcp_f32_e32 v164, v164
	v_rcp_f32_e32 v165, v165
	s_nop 0
	v_mul_f32_e32 v128, v164, v128
	v_mul_f32_e32 v129, v165, v129
	v_mul_f32_e32 v128, v166, v128
	v_mul_f32_e32 v129, v167, v129
	v_cvt_pk_bf16_f32 v128, v128, v128
	v_cvt_pk_bf16_f32 v129, v129, v129
	s_mov_b32 s24, s8
	s_mov_b32 s25, s9
	global_store_short v162, v66, s[24:25] offset:3072
	global_store_short v162, v67, s[24:25] offset:3136
	global_store_short v162, v68, s[24:25] offset:3200
	global_store_short v162, v69, s[24:25] offset:3264
	s_add_u32 s24, s24, 0x1400
	s_addc_u32 s25, s25, 0
	global_store_short v162, v70, s[24:25] offset:3072
	global_store_short v162, v71, s[24:25] offset:3136
	global_store_short v162, v72, s[24:25] offset:3200
	global_store_short v162, v73, s[24:25] offset:3264
	s_add_u32 s24, s24, 0x1400
	s_addc_u32 s25, s25, 0
	global_store_short v162, v74, s[24:25] offset:3072
	global_store_short v162, v75, s[24:25] offset:3136
	global_store_short v162, v76, s[24:25] offset:3200
	global_store_short v162, v77, s[24:25] offset:3264
	s_add_u32 s24, s24, 0x1400
	s_addc_u32 s25, s25, 0
	global_store_short v162, v78, s[24:25] offset:3072
	global_store_short v162, v79, s[24:25] offset:3136
	global_store_short v162, v80, s[24:25] offset:3200
	global_store_short v162, v81, s[24:25] offset:3264
	s_add_u32 s24, s24, 0x6400
	s_addc_u32 s25, s25, 0
	global_store_short v162, v82, s[24:25] offset:3072
	global_store_short v162, v83, s[24:25] offset:3136
	global_store_short v162, v84, s[24:25] offset:3200
	global_store_short v162, v85, s[24:25] offset:3264
	s_add_u32 s24, s24, 0x1400
	s_addc_u32 s25, s25, 0
	global_store_short v162, v86, s[24:25] offset:3072
	global_store_short v162, v87, s[24:25] offset:3136
	global_store_short v162, v88, s[24:25] offset:3200
	global_store_short v162, v89, s[24:25] offset:3264
	s_add_u32 s24, s24, 0x1400
	s_addc_u32 s25, s25, 0
	global_store_short v162, v90, s[24:25] offset:3072
	global_store_short v162, v91, s[24:25] offset:3136
	global_store_short v162, v92, s[24:25] offset:3200
	global_store_short v162, v93, s[24:25] offset:3264
	s_add_u32 s24, s24, 0x1400
	s_addc_u32 s25, s25, 0
	global_store_short v162, v94, s[24:25] offset:3072
	global_store_short v162, v95, s[24:25] offset:3136
	global_store_short v162, v96, s[24:25] offset:3200
	global_store_short v162, v97, s[24:25] offset:3264
	s_add_u32 s24, s24, 0x6400
	s_addc_u32 s25, s25, 0
	global_store_short v162, v98, s[24:25] offset:3072
	global_store_short v162, v99, s[24:25] offset:3136
	global_store_short v162, v100, s[24:25] offset:3200
	global_store_short v162, v101, s[24:25] offset:3264
	s_add_u32 s24, s24, 0x1400
	s_addc_u32 s25, s25, 0
	global_store_short v162, v102, s[24:25] offset:3072
	global_store_short v162, v103, s[24:25] offset:3136
	global_store_short v162, v104, s[24:25] offset:3200
	global_store_short v162, v105, s[24:25] offset:3264
	s_add_u32 s24, s24, 0x1400
	s_addc_u32 s25, s25, 0
	global_store_short v162, v106, s[24:25] offset:3072
	global_store_short v162, v107, s[24:25] offset:3136
	global_store_short v162, v108, s[24:25] offset:3200
	global_store_short v162, v109, s[24:25] offset:3264
	s_add_u32 s24, s24, 0x1400
	s_addc_u32 s25, s25, 0
	global_store_short v162, v110, s[24:25] offset:3072
	global_store_short v162, v111, s[24:25] offset:3136
	global_store_short v162, v112, s[24:25] offset:3200
	global_store_short v162, v113, s[24:25] offset:3264
	s_add_u32 s24, s24, 0x6400
	s_addc_u32 s25, s25, 0
	global_store_short v162, v114, s[24:25] offset:3072
	global_store_short v162, v115, s[24:25] offset:3136
	global_store_short v162, v116, s[24:25] offset:3200
	global_store_short v162, v117, s[24:25] offset:3264
	s_add_u32 s24, s24, 0x1400
	s_addc_u32 s25, s25, 0
	global_store_short v162, v118, s[24:25] offset:3072
	global_store_short v162, v119, s[24:25] offset:3136
	global_store_short v162, v120, s[24:25] offset:3200
	global_store_short v162, v121, s[24:25] offset:3264
	s_add_u32 s24, s24, 0x1400
	s_addc_u32 s25, s25, 0
	global_store_short v162, v122, s[24:25] offset:3072
	global_store_short v162, v123, s[24:25] offset:3136
	global_store_short v162, v124, s[24:25] offset:3200
	global_store_short v162, v125, s[24:25] offset:3264
	s_add_u32 s24, s24, 0x1400
	s_addc_u32 s25, s25, 0
	global_store_short v162, v126, s[24:25] offset:3072
	global_store_short v162, v127, s[24:25] offset:3136
	global_store_short v162, v128, s[24:25] offset:3200
	global_store_short v162, v129, s[24:25] offset:3264
	s_branch .LBB0_276
